# G3 conv epilogue: dropped the hazard pads that followed the empty inline-asm ordering markers (126 wait states per tile)
# baseline (speedup 1.0000x reference)
; __device__ __forceinline__ float bperm_f(int src_lane, float v) { return __builtin_bit_cast(float, __builtin_amdgcn_ds_bpermute(src_lane << 2, __builtin_bit_cast(int, v))); }
;     __device__ __forceinline__ void operator()(Acc& acc, const Unit& u, int wr, int wc, int fr, int fq) const {
;         const int b = u.pm / UPU, j = u.pm % UPU;
;         const int tbase = 252 * j + 126 * wr - 2 + fr;
;         const int ch0 = 128 * u.pn + 32 * wc + 8 * fq;
;         float chain = 0.f;
;         { const int ln = (fq << 4) | fr; f32x4 pq[8];
; #pragma unroll
;           for (int q = 0; q < 8; ++q) { const int t = tbase + 16 * q; const bool ok = (t >= 0) && (t < SEQ); pq[q] = *(const f32x4*)(ssq + (size_t)(b * SEQ + (ok ? t : 0)) * 16 + 4 * fq); }
; #pragma unroll
;           for (int q = 0; q < 8; ++q) {
;             const int t = tbase + 16 * q; const bool ok = (t >= 0) && (t < SEQ);
;             float sq = (pq[q][0] + pq[q][1]) + (pq[q][2] + pq[q][3]); sq += bperm_f(ln ^ 16, sq); sq += bperm_f(ln ^ 32, sq);
;             const float rs = rsqrtf(sq * (1.0f / DM) + EPS);
; #pragma unroll
;             for (int bj = 0; bj < 2; ++bj)
; #pragma unroll
;                 for (int n = 0; n < 2; ++n)
; #pragma unroll
;                     for (int i = 0; i < 4; ++i) { const float v = acc[q >> 2][bj][q & 3][n][i]; acc[q >> 2][bj][q & 3][n][i] = ok ? v * rs : 0.f; }
.LBB0_43:
	s_mul_hi_i32 s21, s20, 0x3e0f83e1
	s_lshr_b32 s27, s21, 31
	s_ashr_i32 s21, s21, 3
	s_add_i32 s21, s21, s27
	s_mul_i32 s27, s21, 33
	s_sub_i32 s20, s20, s27
	s_mulk_i32 s20, 0xfc
	v_add_u32_e32 v198, s20, v194
	v_add_u32_e32 v223, 16, v198
	v_cmp_gt_u32_e64 s[56:57], s97, v198
	v_cmp_gt_u32_e64 s[52:53], s97, v223
	s_lshl_b32 s20, s21, 13
	v_cndmask_b32_e64 v132, 0, v198, s[56:57]
	v_cndmask_b32_e64 v136, 0, v223, s[52:53]
	v_add_u32_e32 v132, s20, v132
	v_add_u32_e32 v136, s20, v136
	v_ashrrev_i32_e32 v133, 31, v132
	v_ashrrev_i32_e32 v137, 31, v136
	v_lshlrev_b64 v[132:133], 6, v[132:133]
	v_lshlrev_b64 v[136:137], 6, v[136:137]
	v_lshl_add_u64 v[132:133], v[146:147], 0, v[132:133]
	v_lshl_add_u64 v[136:137], v[146:147], 0, v[136:137]
	flat_load_dwordx4 v[132:135], v[132:133]
	v_add_u32_e32 v227, 32, v198
	flat_load_dwordx4 v[136:139], v[136:137]
	v_add_u32_e32 v226, 48, v198
	v_cmp_gt_u32_e64 s[54:55], s97, v227
	v_add_u32_e32 v225, 64, v198
	v_cmp_gt_u32_e64 s[50:51], s97, v226
	v_cndmask_b32_e64 v152, 0, v227, s[54:55]
	v_cmp_gt_u32_e64 s[48:49], s97, v225
	v_cndmask_b32_e64 v153, 0, v226, s[50:51]
	v_add_u32_e32 v152, s20, v152
	v_cndmask_b32_e64 v155, 0, v225, s[48:49]
	v_add_u32_e32 v154, s20, v153
	v_ashrrev_i32_e32 v153, 31, v152
	v_add_u32_e32 v156, s20, v155
	v_ashrrev_i32_e32 v155, 31, v154
	v_lshlrev_b64 v[152:153], 6, v[152:153]
	v_lshlrev_b64 v[154:155], 6, v[154:155]
	v_add_u32_e32 v224, 0x50, v198
	v_cmp_gt_u32_e64 s[46:47], s97, v224
	s_mov_b32 s44, 0x358637bd
	v_add_u32_e32 v222, 0x60, v198
	v_add_u32_e32 v199, 0x70, v198
	v_cndmask_b32_e64 v157, 0, v224, s[46:47]
	v_mov_b64_e32 v[188:189], s[44:45]
	v_cmp_gt_u32_e64 s[44:45], s97, v222
	v_cmp_gt_u32_e32 vcc, s97, v199
	v_add_u32_e32 v158, s20, v157
	v_ashrrev_i32_e32 v157, 31, v156
	v_cndmask_b32_e64 v159, 0, v222, s[44:45]
	v_cndmask_b32_e32 v161, 0, v199, vcc
	v_lshlrev_b64 v[156:157], 6, v[156:157]
	s_mov_b32 s90, 0x3a800000
	v_add_u32_e32 v160, s20, v159
	v_add_u32_e32 v162, s20, v161
	v_ashrrev_i32_e32 v159, 31, v158
	v_ashrrev_i32_e32 v161, 31, v160
	v_ashrrev_i32_e32 v163, 31, v162
	v_lshlrev_b64 v[158:159], 6, v[158:159]
	v_lshlrev_b64 v[160:161], 6, v[160:161]
	v_lshlrev_b64 v[162:163], 6, v[162:163]
	s_waitcnt vmcnt(0) lgkmcnt(0)
	v_mov_b32_e32 v174, v133
	v_mov_b32_e32 v175, v134
	v_mov_b32_e32 v133, v135
	v_mov_b32_e32 v134, v137
	v_mov_b32_e32 v135, v138
	v_mov_b32_e32 v137, v139
	v_pk_add_f32 v[132:133], v[174:175], v[132:133]
	v_pk_add_f32 v[134:135], v[134:135], v[136:137]
	v_mov_b32_e32 v137, v132
	v_mov_b32_e32 v136, v134
	v_mov_b32_e32 v132, v135
	v_pk_add_f32 v[132:133], v[136:137], v[132:133]
	v_lshl_add_u64 v[136:137], v[146:147], 0, v[152:153]
	v_lshl_add_u64 v[138:139], v[146:147], 0, v[154:155]
	flat_load_dwordx4 v[190:193], v[136:137]
	flat_load_dwordx4 v[228:231], v[138:139]
	ds_bpermute_b32 v135, v195, v133
	ds_bpermute_b32 v134, v195, v132
	v_lshl_add_u64 v[136:137], v[146:147], 0, v[156:157]
	v_lshl_add_u64 v[138:139], v[146:147], 0, v[158:159]
	v_lshl_add_u64 v[152:153], v[146:147], 0, v[160:161]
	v_lshl_add_u64 v[154:155], v[146:147], 0, v[162:163]
	s_waitcnt lgkmcnt(0)
	v_pk_add_f32 v[132:133], v[132:133], v[134:135]
	ds_bpermute_b32 v135, v196, v133
	ds_bpermute_b32 v134, v196, v132
	s_waitcnt lgkmcnt(0)
	v_pk_add_f32 v[132:133], v[132:133], v[134:135]
	s_nop 0
	v_pk_fma_f32 v[156:157], v[132:133], s[90:91], v[188:189] op_sel_hi:[1,0,0]
	s_nop 0
	v_mul_f32_e32 v132, 0x4b800000, v157
	v_cmp_gt_f32_e64 s[58:59], s29, v157
	s_nop 1
	v_cndmask_b32_e64 v132, v157, v132, s[58:59]
	v_rsq_f32_e32 v157, v132
	flat_load_dwordx4 v[232:235], v[136:137]
	flat_load_dwordx4 v[236:239], v[138:139]
	s_nop 0
	flat_load_dwordx4 v[136:139], v[152:153]
	flat_load_dwordx4 v[132:135], v[154:155]
	v_mul_f32_e32 v152, 0x45800000, v157
	v_cndmask_b32_e64 v153, v157, v152, s[58:59]
	v_mul_f32_e32 v152, v126, v153
	v_mul_f32_e32 v108, v108, v153
	v_mul_f32_e32 v157, v122, v153
	v_cndmask_b32_e64 v122, 0, v152, s[56:57]
	v_cndmask_b32_e64 v152, 0, v108, s[56:57]
	v_mul_f32_e32 v108, v109, v153
	v_mul_f32_e32 v109, 0x4b800000, v156
	v_cmp_gt_f32_e64 s[58:59], s29, v156
	v_mul_f32_e32 v128, v128, v153
	v_mul_f32_e32 v130, v130, v153
	v_cndmask_b32_e64 v109, v156, v109, s[58:59]
	v_rsq_f32_e32 v109, v109
	v_mul_f32_e32 v124, v124, v153
	v_cndmask_b32_e64 v182, 0, v128, s[56:57]
	v_cndmask_b32_e64 v128, 0, v108, s[56:57]
	v_mul_f32_e32 v108, v110, v153
	v_cndmask_b32_e64 v160, 0, v130, s[56:57]
	v_cndmask_b32_e64 v130, 0, v124, s[56:57]
	v_cndmask_b32_e64 v124, 0, v108, s[56:57]
	v_mul_f32_e32 v108, v111, v153
	v_cndmask_b32_e64 v110, 0, v108, s[56:57]
	v_mul_f32_e32 v108, 0x45800000, v109
	v_cndmask_b32_e64 v108, v109, v108, s[58:59]
	v_mul_f32_e32 v109, v116, v108
	v_cndmask_b32_e64 v187, 0, v109, s[52:53]
	v_mul_f32_e32 v109, v117, v108
	v_cndmask_b32_e64 v181, 0, v109, s[52:53]
	v_mul_f32_e32 v109, v118, v108
	v_cndmask_b32_e64 v175, 0, v109, s[52:53]
	v_mul_f32_e32 v109, v119, v108
	v_cndmask_b32_e64 v162, 0, v157, s[56:57]
	v_cndmask_b32_e64 v157, 0, v109, s[52:53]
	v_mul_f32_e32 v109, v112, v108
	v_cndmask_b32_e64 v119, 0, v109, s[52:53]
	v_mul_f32_e32 v109, v113, v108
	v_mul_f32_e32 v104, v104, v108
	v_cndmask_b32_e64 v117, 0, v109, s[52:53]
	v_mul_f32_e32 v109, v114, v108
	v_cndmask_b32_e64 v186, 0, v104, s[52:53]
	v_mul_f32_e32 v104, v105, v108
	v_cndmask_b32_e64 v113, 0, v109, s[52:53]
	v_mul_f32_e32 v109, v115, v108
	v_cndmask_b32_e64 v180, 0, v104, s[52:53]
	v_mul_f32_e32 v106, v106, v108
	v_cndmask_b32_e64 v174, 0, v106, s[52:53]
	v_mul_f32_e32 v106, v107, v108
	v_cndmask_b32_e64 v156, 0, v106, s[52:53]
	v_mul_f32_e32 v92, v92, v108
	v_cndmask_b32_e64 v118, 0, v92, s[52:53]
	v_mul_f32_e32 v92, v93, v108
	v_mul_f32_e32 v121, v121, v153
	s_waitcnt vmcnt(0)
; __device__ __forceinline__ float bperm_f(int src_lane, float v) { return __builtin_bit_cast(float, __builtin_amdgcn_ds_bpermute(src_lane << 2, __builtin_bit_cast(int, v))); }
;     __device__ __forceinline__ void operator()(Acc& acc, const Unit& u, int wr, int wc, int fr, int fq) const {
;     ...
;           for (int q = 0; q < 8; ++q) { const int t = tbase + 16 * q; const bool ok = (t >= 0) && (t < SEQ); pq[q] = *(const f32x4*)(ssq + (size_t)(b * SEQ + (ok ? t : 0)) * 16 + 4 * fq); }
; #pragma unroll
;           for (int q = 0; q < 8; ++q) {
;             const int t = tbase + 16 * q; const bool ok = (t >= 0) && (t < SEQ);
;             float sq = (pq[q][0] + pq[q][1]) + (pq[q][2] + pq[q][3]); sq += bperm_f(ln ^ 16, sq); sq += bperm_f(ln ^ 32, sq);
;             const float rs = rsqrtf(sq * (1.0f / DM) + EPS);
; #pragma unroll
;             for (int bj = 0; bj < 2; ++bj)
; #pragma unroll
;                 for (int n = 0; n < 2; ++n)
; #pragma unroll
;                     for (int i = 0; i < 4; ++i) { const float v = acc[q >> 2][bj][q & 3][n][i]; acc[q >> 2][bj][q & 3][n][i] = ok ? v * rs : 0.f; }
	v_mov_b32_e32 v104, v191
	v_mov_b32_e32 v105, v192
	v_mov_b32_e32 v191, v193
	v_mov_b32_e32 v114, v229
	v_mov_b32_e32 v115, v230
	v_mov_b32_e32 v229, v231
	v_pk_add_f32 v[104:105], v[104:105], v[190:191]
	v_pk_add_f32 v[114:115], v[114:115], v[228:229]
	v_mov_b32_e32 v191, v104
	v_mov_b32_e32 v190, v114
	v_mov_b32_e32 v104, v115
	v_pk_add_f32 v[104:105], v[190:191], v[104:105]
	ds_bpermute_b32 v115, v195, v105
	ds_bpermute_b32 v114, v195, v104
	v_cndmask_b32_e64 v116, 0, v92, s[52:53]
	v_mul_f32_e32 v129, v129, v153
	v_mul_f32_e32 v131, v131, v153
	v_mul_f32_e32 v125, v125, v153
	s_waitcnt lgkmcnt(0)
	v_pk_add_f32 v[104:105], v[104:105], v[114:115]
	ds_bpermute_b32 v107, v196, v105
	ds_bpermute_b32 v106, v196, v104
	v_mul_f32_e32 v127, v127, v153
	v_mul_f32_e32 v155, v120, v153
	v_cndmask_b32_e64 v178, 0, v121, s[56:57]
	v_mul_f32_e32 v121, v123, v153
	s_waitcnt lgkmcnt(0)
	v_pk_add_f32 v[92:93], v[104:105], v[106:107]
	v_cndmask_b32_e64 v176, 0, v129, s[56:57]
	v_pk_fma_f32 v[92:93], v[92:93], s[90:91], v[188:189] op_sel_hi:[1,0,0]
	v_cndmask_b32_e64 v154, 0, v131, s[56:57]
	v_cndmask_b32_e64 v126, 0, v125, s[56:57]
	v_cndmask_b32_e64 v120, 0, v127, s[56:57]
	v_cndmask_b32_e64 v184, 0, v155, s[56:57]
	v_cndmask_b32_e64 v158, 0, v121, s[56:57]
	v_mul_f32_e32 v104, 0x4b800000, v93
	v_cmp_gt_f32_e64 s[56:57], s29, v93
	v_mul_f32_e32 v94, v94, v108
	v_cndmask_b32_e64 v112, 0, v94, s[52:53]
	v_cndmask_b32_e64 v93, v93, v104, s[56:57]
	v_rsq_f32_e32 v93, v93
	v_mul_f32_e32 v94, v95, v108
	v_cndmask_b32_e64 v108, 0, v94, s[52:53]
	v_cndmask_b32_e64 v109, 0, v109, s[52:53]
	v_mul_f32_e32 v94, 0x45800000, v93
	v_cndmask_b32_e64 v111, v93, v94, s[56:57]
	v_mul_f32_e32 v76, v76, v111
	v_mul_f32_e32 v93, v100, v111
	v_cndmask_b32_e64 v100, 0, v76, s[54:55]
	v_mul_f32_e32 v76, v77, v111
	v_mul_f32_e32 v77, 0x4b800000, v92
	v_cmp_gt_f32_e64 s[52:53], s29, v92
	v_cndmask_b32_e64 v115, 0, v93, s[54:55]
	v_mul_f32_e32 v93, v101, v111
	v_cndmask_b32_e64 v77, v92, v77, s[52:53]
	v_cndmask_b32_e64 v107, 0, v93, s[54:55]
	v_mul_f32_e32 v93, v102, v111
	v_rsq_f32_e32 v77, v77
	v_cndmask_b32_e64 v105, 0, v93, s[54:55]
	v_mul_f32_e32 v93, v103, v111
	v_cndmask_b32_e64 v103, 0, v93, s[54:55]
	v_mul_f32_e32 v93, v96, v111
	v_cndmask_b32_e64 v96, 0, v76, s[54:55]
	v_mul_f32_e32 v76, v78, v111
	v_cndmask_b32_e64 v94, 0, v76, s[54:55]
	v_mul_f32_e32 v76, v79, v111
	v_cndmask_b32_e64 v92, 0, v76, s[54:55]
	v_mul_f32_e32 v76, 0x45800000, v77
	v_cndmask_b32_e64 v101, 0, v93, s[54:55]
	v_mul_f32_e32 v93, v97, v111
	v_mul_f32_e32 v88, v88, v111
	v_cndmask_b32_e64 v76, v77, v76, s[52:53]
	v_cndmask_b32_e64 v97, 0, v93, s[54:55]
	v_mul_f32_e32 v93, v98, v111
	v_cndmask_b32_e64 v114, 0, v88, s[54:55]
	v_mul_f32_e32 v88, v89, v111
	v_mul_f32_e32 v77, v84, v76
	v_cndmask_b32_e64 v95, 0, v93, s[54:55]
	v_mul_f32_e32 v93, v99, v111
	v_cndmask_b32_e64 v106, 0, v88, s[54:55]
	v_mul_f32_e32 v88, v90, v111
	v_cndmask_b32_e64 v99, 0, v77, s[50:51]
	v_mul_f32_e32 v77, v85, v76
	v_cndmask_b32_e64 v104, 0, v88, s[54:55]
	v_mul_f32_e32 v88, v91, v111
	v_cndmask_b32_e64 v91, 0, v77, s[50:51]
	v_mul_f32_e32 v77, v86, v76
	v_cndmask_b32_e64 v89, 0, v77, s[50:51]
	v_mul_f32_e32 v77, v87, v76
	v_cndmask_b32_e64 v87, 0, v77, s[50:51]
	v_mul_f32_e32 v77, v80, v76
	v_cndmask_b32_e64 v85, 0, v77, s[50:51]
	v_mul_f32_e32 v77, v81, v76
	v_mul_f32_e32 v72, v72, v76
	v_cndmask_b32_e64 v81, 0, v77, s[50:51]
	v_mul_f32_e32 v77, v82, v76
	v_cndmask_b32_e64 v98, 0, v72, s[50:51]
	v_mul_f32_e32 v72, v73, v76
	v_cndmask_b32_e64 v79, 0, v77, s[50:51]
	v_mul_f32_e32 v77, v83, v76
	v_cndmask_b32_e64 v90, 0, v72, s[50:51]
	v_mov_b32_e32 v72, v233
	v_mov_b32_e32 v73, v234
	v_mov_b32_e32 v233, v235
	v_mov_b32_e32 v82, v237
	v_mov_b32_e32 v83, v238
	v_mov_b32_e32 v237, v239
	v_pk_add_f32 v[72:73], v[72:73], v[232:233]
	v_pk_add_f32 v[82:83], v[82:83], v[236:237]
	v_mov_b32_e32 v191, v72
	v_mov_b32_e32 v190, v82
	v_mov_b32_e32 v72, v83
	v_pk_add_f32 v[72:73], v[190:191], v[72:73]
	ds_bpermute_b32 v83, v195, v73
	ds_bpermute_b32 v82, v195, v72
	v_mul_f32_e32 v74, v74, v76
	v_cndmask_b32_e64 v102, 0, v88, s[54:55]
	v_cndmask_b32_e64 v88, 0, v74, s[50:51]
	v_mul_f32_e32 v74, v75, v76
	s_waitcnt lgkmcnt(0)
	v_pk_add_f32 v[72:73], v[72:73], v[82:83]
	v_cndmask_b32_e64 v86, 0, v74, s[50:51]
	ds_bpermute_b32 v75, v196, v73
	ds_bpermute_b32 v74, v196, v72
	v_mul_f32_e32 v68, v68, v76
	v_cndmask_b32_e64 v84, 0, v68, s[50:51]
	v_mul_f32_e32 v68, v69, v76
	v_cndmask_b32_e64 v80, 0, v68, s[50:51]
	s_waitcnt lgkmcnt(0)
; __device__ __forceinline__ float bperm_f(int src_lane, float v) { return __builtin_bit_cast(float, __builtin_amdgcn_ds_bpermute(src_lane << 2, __builtin_bit_cast(int, v))); }
;     __device__ __forceinline__ void operator()(Acc& acc, const Unit& u, int wr, int wc, int fr, int fq) const {
;     ...
;           for (int q = 0; q < 8; ++q) { const int t = tbase + 16 * q; const bool ok = (t >= 0) && (t < SEQ); pq[q] = *(const f32x4*)(ssq + (size_t)(b * SEQ + (ok ? t : 0)) * 16 + 4 * fq); }
; #pragma unroll
;           for (int q = 0; q < 8; ++q) {
;             const int t = tbase + 16 * q; const bool ok = (t >= 0) && (t < SEQ);
;             float sq = (pq[q][0] + pq[q][1]) + (pq[q][2] + pq[q][3]); sq += bperm_f(ln ^ 16, sq); sq += bperm_f(ln ^ 32, sq);
;             const float rs = rsqrtf(sq * (1.0f / DM) + EPS);
; #pragma unroll
;             for (int bj = 0; bj < 2; ++bj)
; #pragma unroll
;                 for (int n = 0; n < 2; ++n)
; #pragma unroll
;                     for (int i = 0; i < 4; ++i) { const float v = acc[q >> 2][bj][q & 3][n][i]; acc[q >> 2][bj][q & 3][n][i] = ok ? v * rs : 0.f; }
	v_pk_add_f32 v[68:69], v[72:73], v[74:75]
	v_mul_f32_e32 v70, v70, v76
	v_pk_fma_f32 v[82:83], v[68:69], s[90:91], v[188:189] op_sel_hi:[1,0,0]
	v_mul_f32_e32 v69, v71, v76
	v_mul_f32_e32 v68, 0x4b800000, v83
	v_cmp_gt_f32_e64 s[52:53], s29, v83
	v_cndmask_b32_e64 v76, 0, v69, s[50:51]
	v_cndmask_b32_e64 v77, 0, v77, s[50:51]
	v_cndmask_b32_e64 v68, v83, v68, s[52:53]
	v_rsq_f32_e32 v68, v68
	v_cndmask_b32_e64 v78, 0, v70, s[50:51]
	v_cmp_gt_f32_e64 s[50:51], s29, v82
	v_cndmask_b32_e64 v93, 0, v93, s[54:55]
	v_mul_f32_e32 v69, 0x45800000, v68
	v_cndmask_b32_e64 v83, v68, v69, s[52:53]
	v_mul_f32_e32 v44, v44, v83
	v_cndmask_b32_e64 v68, 0, v44, s[48:49]
	v_mul_f32_e32 v44, v45, v83
	v_mul_f32_e32 v45, 0x4b800000, v82
	v_mul_f32_e32 v64, v64, v83
	v_cndmask_b32_e64 v45, v82, v45, s[50:51]
	v_cndmask_b32_e64 v191, 0, v64, s[48:49]
	v_mul_f32_e32 v64, v65, v83
	v_mul_f32_e32 v60, v60, v83
	v_rsq_f32_e32 v45, v45
	v_cndmask_b32_e64 v75, 0, v64, s[48:49]
	v_mul_f32_e32 v64, v66, v83
	v_cndmask_b32_e64 v69, 0, v60, s[48:49]
	v_mul_f32_e32 v60, v61, v83
	v_cndmask_b32_e64 v73, 0, v64, s[48:49]
	v_mul_f32_e32 v64, v67, v83
	v_cndmask_b32_e64 v67, 0, v60, s[48:49]
	v_mul_f32_e32 v60, v62, v83
	v_cndmask_b32_e64 v66, 0, v44, s[48:49]
	v_mul_f32_e32 v44, v46, v83
	v_cndmask_b32_e64 v71, 0, v64, s[48:49]
	v_cndmask_b32_e64 v65, 0, v60, s[48:49]
	v_mul_f32_e32 v60, v63, v83
	v_cndmask_b32_e64 v64, 0, v44, s[48:49]
	v_mul_f32_e32 v44, v47, v83
	v_cndmask_b32_e64 v61, 0, v60, s[48:49]
	v_cndmask_b32_e64 v60, 0, v44, s[48:49]
	v_mul_f32_e32 v44, 0x45800000, v45
	v_mul_f32_e32 v56, v56, v83
	v_cndmask_b32_e64 v44, v45, v44, s[50:51]
	v_cndmask_b32_e64 v190, 0, v56, s[48:49]
	v_mul_f32_e32 v56, v57, v83
	v_mul_f32_e32 v45, v52, v44
	v_cndmask_b32_e64 v74, 0, v56, s[48:49]
	v_mul_f32_e32 v56, v58, v83
	v_cndmask_b32_e64 v193, 0, v45, s[46:47]
	v_mul_f32_e32 v45, v53, v44
	v_cndmask_b32_e64 v72, 0, v56, s[48:49]
	v_mul_f32_e32 v56, v59, v83
	v_cndmask_b32_e64 v59, 0, v45, s[46:47]
	v_mul_f32_e32 v45, v54, v44
	v_cndmask_b32_e64 v57, 0, v45, s[46:47]
	v_mul_f32_e32 v45, v55, v44
	v_cndmask_b32_e64 v55, 0, v45, s[46:47]
	v_mul_f32_e32 v45, v48, v44
	v_cndmask_b32_e64 v53, 0, v45, s[46:47]
	v_mul_f32_e32 v45, v49, v44
	v_mul_f32_e32 v40, v40, v44
	v_cndmask_b32_e64 v49, 0, v45, s[46:47]
	v_mul_f32_e32 v45, v50, v44
	v_cndmask_b32_e64 v192, 0, v40, s[46:47]
	v_mul_f32_e32 v40, v41, v44
	v_cndmask_b32_e64 v47, 0, v45, s[46:47]
	v_mul_f32_e32 v45, v51, v44
	v_cndmask_b32_e64 v58, 0, v40, s[46:47]
	v_mov_b32_e32 v40, v137
	v_mov_b32_e32 v41, v138
	v_mov_b32_e32 v137, v139
	v_mov_b32_e32 v50, v133
	v_mov_b32_e32 v51, v134
	v_mov_b32_e32 v133, v135
	v_pk_add_f32 v[40:41], v[40:41], v[136:137]
	v_pk_add_f32 v[50:51], v[50:51], v[132:133]
	v_mov_b32_e32 v63, v40
	v_mov_b32_e32 v62, v50
	v_mov_b32_e32 v40, v51
	v_pk_add_f32 v[40:41], v[62:63], v[40:41]
	ds_bpermute_b32 v51, v195, v41
	ds_bpermute_b32 v50, v195, v40
	v_mul_f32_e32 v42, v42, v44
	v_cndmask_b32_e64 v70, 0, v56, s[48:49]
	v_cndmask_b32_e64 v56, 0, v42, s[46:47]
	v_mul_f32_e32 v42, v43, v44
	s_waitcnt lgkmcnt(0)
	v_pk_add_f32 v[40:41], v[40:41], v[50:51]
	v_cndmask_b32_e64 v54, 0, v42, s[46:47]
	ds_bpermute_b32 v43, v196, v41
	ds_bpermute_b32 v42, v196, v40
	v_mul_f32_e32 v28, v28, v44
	v_cndmask_b32_e64 v52, 0, v28, s[46:47]
	v_mul_f32_e32 v28, v29, v44
	v_cndmask_b32_e64 v48, 0, v28, s[46:47]
	s_waitcnt lgkmcnt(0)
	v_pk_add_f32 v[28:29], v[40:41], v[42:43]
	v_mul_f32_e32 v30, v30, v44
	v_pk_fma_f32 v[28:29], v[28:29], s[90:91], v[188:189] op_sel_hi:[1,0,0]
	v_cndmask_b32_e64 v46, 0, v30, s[46:47]
	v_mul_f32_e32 v40, 0x4b800000, v29
	v_cmp_gt_f32_e64 s[48:49], s29, v29
	v_mul_f32_e32 v30, v31, v44
	v_cndmask_b32_e64 v44, 0, v30, s[46:47]
	v_cndmask_b32_e64 v29, v29, v40, s[48:49]
	v_rsq_f32_e32 v29, v29
	v_cndmask_b32_e64 v45, 0, v45, s[46:47]
	v_cmp_gt_f32_e64 s[46:47], s29, v28
	v_mul_f32_e32 v30, 0x45800000, v29
	v_cndmask_b32_e64 v40, v29, v30, s[48:49]
	v_mul_f32_e32 v12, v12, v40
	v_mul_f32_e32 v29, v36, v40
	v_cndmask_b32_e64 v36, 0, v12, s[44:45]
	v_mul_f32_e32 v12, v13, v40
	v_mul_f32_e32 v13, 0x4b800000, v28
	v_cndmask_b32_e64 v133, 0, v29, s[44:45]
	v_mul_f32_e32 v29, v37, v40
	v_cndmask_b32_e64 v13, v28, v13, s[46:47]
	v_cndmask_b32_e64 v63, 0, v29, s[44:45]
	v_mul_f32_e32 v29, v38, v40
	v_rsq_f32_e32 v13, v13
	v_cndmask_b32_e64 v43, 0, v29, s[44:45]
	v_mul_f32_e32 v29, v39, v40
	v_cndmask_b32_e64 v39, 0, v29, s[44:45]
	v_mul_f32_e32 v29, v32, v40
	v_cndmask_b32_e64 v32, 0, v12, s[44:45]
	v_mul_f32_e32 v12, v14, v40
	v_cndmask_b32_e64 v30, 0, v12, s[44:45]
	v_mul_f32_e32 v12, v15, v40
	v_cndmask_b32_e64 v28, 0, v12, s[44:45]
	v_mul_f32_e32 v12, 0x45800000, v13
	v_cndmask_b32_e64 v12, v13, v12, s[46:47]
	v_mul_f32_e32 v13, v20, v12
	v_cndmask_b32_e32 v135, 0, v13, vcc
	v_mul_f32_e32 v13, v21, v12
	v_cndmask_b32_e32 v83, 0, v13, vcc
	v_mul_f32_e32 v13, v22, v12
	v_cndmask_b32_e64 v37, 0, v29, s[44:45]
	v_mul_f32_e32 v29, v33, v40
	v_mul_f32_e32 v24, v24, v40
	v_cndmask_b32_e32 v51, 0, v13, vcc
	v_mul_f32_e32 v13, v23, v12
	v_cndmask_b32_e64 v33, 0, v29, s[44:45]
	v_mul_f32_e32 v29, v34, v40
	v_cndmask_b32_e64 v132, 0, v24, s[44:45]
	v_mul_f32_e32 v24, v25, v40
	v_cndmask_b32_e32 v41, 0, v13, vcc
	v_mul_f32_e32 v13, v16, v12
	v_mul_f32_e32 v8, v8, v12
	v_mul_f32_e32 v4, v4, v12
	v_cndmask_b32_e64 v31, 0, v29, s[44:45]
	v_mul_f32_e32 v29, v35, v40
	v_cndmask_b32_e64 v62, 0, v24, s[44:45]
	v_mul_f32_e32 v24, v26, v40
	v_cndmask_b32_e32 v35, 0, v13, vcc
	v_mul_f32_e32 v13, v17, v12
	v_cndmask_b32_e32 v134, 0, v8, vcc
	v_mul_f32_e32 v8, v9, v12
	v_cndmask_b32_e32 v34, 0, v4, vcc
	v_mul_f32_e32 v4, v5, v12
; __device__ __forceinline__ float sigmoidf_(float x) { return __builtin_amdgcn_rcpf(1.0f + __expf(-x)); }
; template <int N> __device__ __forceinline__ float dpp_ror(float v) { return __builtin_bit_cast(float, __builtin_amdgcn_update_dpp(0, __builtin_bit_cast(int, v), 0x120 + N, 0xf, 0xf, false)); }
;     __device__ __forceinline__ void operator()(Acc& acc, const Unit& u, int wr, int wc, int fr, int fq) const {
;     ...
;             float sq = (pq[q][0] + pq[q][1]) + (pq[q][2] + pq[q][3]); sq += bperm_f(ln ^ 16, sq); sq += bperm_f(ln ^ 32, sq);
;             const float rs = rsqrtf(sq * (1.0f / DM) + EPS);
; #pragma unroll
;             for (int bj = 0; bj < 2; ++bj)
; #pragma unroll
;                 for (int n = 0; n < 2; ++n)
; #pragma unroll
;                     for (int i = 0; i < 4; ++i) { const float v = acc[q >> 2][bj][q & 3][n][i]; acc[q >> 2][bj][q & 3][n][i] = ok ? v * rs : 0.f; }
;     ...
;         for (int n = 0; n < 2; ++n) {
; #pragma unroll
;             for (int i = 0; i < 4; ++i) {
;                 const int cg_ = ch0 + 4 * n + i, cv_ = DFF + cg_;
;                 const float g0 = cw[cg_], g1 = cw[NUP + cg_], g2 = cw[2 * NUP + cg_], gb = cb[cg_];
;                 const float v0 = cw[cv_], v1 = cw[NUP + cv_], v2 = cw[2 * NUP + cv_], vb = cb[cv_];
;                 float pg1 = 0.f, pg2 = 0.f, pv1 = 0.f, pv2 = 0.f;
; #pragma unroll
;                 for (int q = 0; q < 8; ++q) {
;                     float cgv = acc[q >> 2][0][q & 3][n][i], cvv = acc[q >> 2][1][q & 3][n][i];
;                     asm volatile("" : "+v"(cgv), "+v"(cvv) : "v"(chain));
;                     const float tg1 = dpp_ror<1>(cgv), tg2 = dpp_ror<2>(cgv), tv1 = dpp_ror<1>(cvv), tv2 = dpp_ror<2>(cvv);
;                     const float sg1 = fr >= 1 ? tg1 : pg1, sg2 = fr >= 2 ? tg2 : pg2, sv1 = fr >= 1 ? tv1 : pv1, sv2 = fr >= 2 ? tv2 : pv2;
;                     const float gg = gb + g0 * sg2 + g1 * sg1 + g2 * cgv;
;                     const float vv = vb + v0 * sv2 + v1 * sv1 + v2 * cvv;
;                     chain = gg * sigmoidf_(gg) * vv; acc[q >> 2][0][q & 3][n][i] = chain;
;                     pg1 = tg1; pg2 = tg2; pv1 = tv1; pv2 = tv2;
;                 }
;                 __builtin_amdgcn_sched_barrier(0);
;             }
	v_cndmask_b32_e64 v42, 0, v24, s[44:45]
	v_mul_f32_e32 v24, v27, v40
	v_cndmask_b32_e32 v27, 0, v13, vcc
	v_mul_f32_e32 v13, v18, v12
	v_cndmask_b32_e32 v82, 0, v8, vcc
	v_mul_f32_e32 v8, v10, v12
	v_cndmask_b32_e32 v26, 0, v4, vcc
	v_mul_f32_e32 v4, v6, v12
	v_cndmask_b32_e32 v15, 0, v13, vcc
	v_mul_f32_e32 v13, v19, v12
	v_cndmask_b32_e32 v50, 0, v8, vcc
	v_mul_f32_e32 v8, v11, v12
	v_cndmask_b32_e32 v14, 0, v4, vcc
	v_mul_f32_e32 v4, v7, v12
	v_cndmask_b32_e64 v29, 0, v29, s[44:45]
	v_cndmask_b32_e64 v38, 0, v24, s[44:45]
	v_cndmask_b32_e32 v13, 0, v13, vcc
	v_cndmask_b32_e32 v40, 0, v8, vcc
	v_cndmask_b32_e32 v12, 0, v4, vcc
	v_lshl_or_b32 v4, s34, 7, v2
	v_ashrrev_i32_e32 v5, 31, v4
	v_lshlrev_b64 v[16:17], 2, v[4:5]
	v_lshl_add_u64 v[6:7], s[36:37], 0, v[16:17]
	s_movk_i32 s21, 0x5000
	v_add_co_u32_e32 v8, vcc, s21, v6
	s_mov_b32 s21, 0xb000
	s_nop 0
	v_addc_co_u32_e32 v9, vcc, 0, v7, vcc
	v_add_co_u32_e32 v10, vcc, s21, v6
	v_lshl_add_u64 v[16:17], s[60:61], 0, v[16:17]
	s_nop 0
	v_addc_co_u32_e32 v11, vcc, 0, v7, vcc
	global_load_dword v139, v[6:7], off
	global_load_dword v137, v[8:9], off offset:2048
	global_load_dword v136, v[10:11], off
	global_load_dword v189, v[16:17], off
	v_add_co_u32_e32 v18, vcc, s97, v6
	s_mov_b32 s21, 0xd000
	s_nop 0
	v_addc_co_u32_e32 v19, vcc, 0, v7, vcc
	v_add_co_u32_e32 v22, vcc, s80, v6
	global_load_dword v138, v[18:19], off offset:3072
	s_nop 0
	v_addc_co_u32_e32 v23, vcc, 0, v7, vcc
	v_add_co_u32_e32 v20, vcc, s97, v16
	s_nop 0
	s_nop 0
	v_addc_co_u32_e32 v21, vcc, 0, v17, vcc
	v_add_co_u32_e32 v24, vcc, s21, v6
	global_load_dword v188, v[20:21], off offset:3072
	s_nop 0
	v_addc_co_u32_e32 v25, vcc, 0, v7, vcc
	global_load_dword v229, v[22:23], off offset:1024
	global_load_dword v228, v[24:25], off offset:3072
	s_nop 0
	v_mov_b32_dpp v111, v182 row_ror:1 row_mask:0xf bank_mask:0xf
	v_mov_b32_dpp v121, v182 row_ror:2 row_mask:0xf bank_mask:0xf
	v_cndmask_b32_e64 v183, v111, 0, s[38:39]
	v_cndmask_b32_e64 v155, 0, v121, s[40:41]
	v_mov_b32_dpp v123, v184 row_ror:1 row_mask:0xf bank_mask:0xf
	v_mov_b32_dpp v125, v184 row_ror:2 row_mask:0xf bank_mask:0xf
	v_cndmask_b32_e64 v185, v123, 0, s[38:39]
	v_cndmask_b32_e64 v159, 0, v125, s[40:41]
	s_waitcnt vmcnt(5)
	v_pk_mul_f32 v[182:183], v[136:137], v[182:183]
	s_waitcnt vmcnt(4)
	v_fma_f32 v155, v139, v155, v189
	v_add_f32_e32 v155, v183, v155
	v_add_f32_e32 v155, v182, v155
	v_mul_f32_e32 v161, 0xbfb8aa3b, v155
	v_exp_f32_e32 v161, v161
	v_mov_b32_e32 v183, v136
	v_add_f32_e32 v136, 1.0, v161
	v_rcp_f32_e32 v161, v136
	s_waitcnt vmcnt(2)
	v_fma_f32 v159, v138, v159, v188
	v_mul_f32_e32 v155, v155, v161
	s_waitcnt vmcnt(1)
	v_mov_b32_e32 v136, v229
	s_waitcnt vmcnt(0)
	v_pk_mul_f32 v[184:185], v[228:229], v[184:185]
	v_mov_b32_e32 v182, v228
	v_add_f32_e32 v159, v185, v159
	v_add_f32_e32 v159, v184, v159
	v_mul_f32_e32 v184, v159, v155
	v_mov_b32_dpp v129, v187 row_ror:2 row_mask:0xf bank_mask:0xf
	v_mov_b32_dpp v153, v186 row_ror:2 row_mask:0xf bank_mask:0xf
	v_mov_b32_dpp v127, v187 row_ror:1 row_mask:0xf bank_mask:0xf
	v_mov_b32_dpp v131, v186 row_ror:1 row_mask:0xf bank_mask:0xf
	v_cndmask_b32_e64 v231, v121, v129, s[40:41]
	v_cndmask_b32_e64 v230, v125, v153, s[40:41]
	v_cndmask_b32_e64 v229, v127, v111, s[38:39]
	v_cndmask_b32_e64 v228, v131, v123, s[38:39]
	v_pk_fma_f32 v[230:231], v[138:139], v[230:231], v[188:189]
	v_pk_fma_f32 v[228:229], v[136:137], v[228:229], v[230:231]
	v_pk_fma_f32 v[186:187], v[182:183], v[186:187], v[228:229]
	v_mul_f32_e32 v111, 0xbfb8aa3b, v187
	v_exp_f32_e32 v111, v111
	s_nop 0
	v_add_f32_e32 v111, 1.0, v111
	v_rcp_f32_e32 v111, v111
	s_nop 0
	v_mul_f32_e32 v111, v187, v111
	v_mul_f32_e32 v185, v186, v111
	v_mov_b32_dpp v123, v115 row_ror:2 row_mask:0xf bank_mask:0xf
	v_mov_b32_dpp v155, v114 row_ror:2 row_mask:0xf bank_mask:0xf
	v_mov_b32_dpp v121, v115 row_ror:1 row_mask:0xf bank_mask:0xf
	v_mov_b32_dpp v125, v114 row_ror:1 row_mask:0xf bank_mask:0xf
	v_cndmask_b32_e64 v229, v129, v123, s[40:41]
	v_cndmask_b32_e64 v228, v153, v155, s[40:41]
	v_cndmask_b32_e64 v187, v121, v127, s[38:39]
	v_cndmask_b32_e64 v186, v125, v131, s[38:39]
	v_pk_fma_f32 v[228:229], v[138:139], v[228:229], v[188:189]
	v_pk_fma_f32 v[186:187], v[136:137], v[186:187], v[228:229]
	v_pk_fma_f32 v[114:115], v[182:183], v[114:115], v[186:187]
	v_mul_f32_e32 v111, 0xbfb8aa3b, v115
	v_exp_f32_e32 v111, v111
	s_nop 0
	v_add_f32_e32 v111, 1.0, v111
	v_rcp_f32_e32 v111, v111
	s_nop 0
	v_mul_f32_e32 v111, v115, v111
	v_mul_f32_e32 v186, v114, v111
	v_mov_b32_dpp v129, v99 row_ror:2 row_mask:0xf bank_mask:0xf
	v_mov_b32_dpp v153, v98 row_ror:2 row_mask:0xf bank_mask:0xf
	v_mov_b32_dpp v127, v99 row_ror:1 row_mask:0xf bank_mask:0xf
	v_mov_b32_dpp v131, v98 row_ror:1 row_mask:0xf bank_mask:0xf
	v_cndmask_b32_e64 v229, v123, v129, s[40:41]
	v_cndmask_b32_e64 v228, v155, v153, s[40:41]
	v_cndmask_b32_e64 v115, v127, v121, s[38:39]
	v_cndmask_b32_e64 v114, v131, v125, s[38:39]
	v_pk_fma_f32 v[228:229], v[138:139], v[228:229], v[188:189]
	v_pk_fma_f32 v[114:115], v[136:137], v[114:115], v[228:229]
	v_pk_fma_f32 v[98:99], v[182:183], v[98:99], v[114:115]
	v_mul_f32_e32 v111, 0xbfb8aa3b, v99
	v_exp_f32_e32 v111, v111
	s_nop 0
	v_add_f32_e32 v111, 1.0, v111
	v_rcp_f32_e32 v111, v111
	s_nop 0
	v_mul_f32_e32 v99, v99, v111
	v_mul_f32_e32 v187, v98, v99
	v_mov_b32_dpp v123, v191 row_ror:2 row_mask:0xf bank_mask:0xf
	v_mov_b32_dpp v155, v190 row_ror:2 row_mask:0xf bank_mask:0xf
	v_mov_b32_dpp v121, v191 row_ror:1 row_mask:0xf bank_mask:0xf
	v_mov_b32_dpp v125, v190 row_ror:1 row_mask:0xf bank_mask:0xf
	v_cndmask_b32_e64 v115, v129, v123, s[40:41]
; __device__ __forceinline__ float sigmoidf_(float x) { return __builtin_amdgcn_rcpf(1.0f + __expf(-x)); }
; template <int N> __device__ __forceinline__ float dpp_ror(float v) { return __builtin_bit_cast(float, __builtin_amdgcn_update_dpp(0, __builtin_bit_cast(int, v), 0x120 + N, 0xf, 0xf, false)); }
;     __device__ __forceinline__ void operator()(Acc& acc, const Unit& u, int wr, int wc, int fr, int fq) const {
;     ...
;         for (int n = 0; n < 2; ++n) {
; #pragma unroll
;             for (int i = 0; i < 4; ++i) {
;                 const int cg_ = ch0 + 4 * n + i, cv_ = DFF + cg_;
;                 const float g0 = cw[cg_], g1 = cw[NUP + cg_], g2 = cw[2 * NUP + cg_], gb = cb[cg_];
;                 const float v0 = cw[cv_], v1 = cw[NUP + cv_], v2 = cw[2 * NUP + cv_], vb = cb[cv_];
;                 float pg1 = 0.f, pg2 = 0.f, pv1 = 0.f, pv2 = 0.f;
; #pragma unroll
;                 for (int q = 0; q < 8; ++q) {
;                     float cgv = acc[q >> 2][0][q & 3][n][i], cvv = acc[q >> 2][1][q & 3][n][i];
;                     asm volatile("" : "+v"(cgv), "+v"(cvv) : "v"(chain));
;                     const float tg1 = dpp_ror<1>(cgv), tg2 = dpp_ror<2>(cgv), tv1 = dpp_ror<1>(cvv), tv2 = dpp_ror<2>(cvv);
;                     const float sg1 = fr >= 1 ? tg1 : pg1, sg2 = fr >= 2 ? tg2 : pg2, sv1 = fr >= 1 ? tv1 : pv1, sv2 = fr >= 2 ? tv2 : pv2;
;                     const float gg = gb + g0 * sg2 + g1 * sg1 + g2 * cgv;
;                     const float vv = vb + v0 * sv2 + v1 * sv1 + v2 * cvv;
;                     chain = gg * sigmoidf_(gg) * vv; acc[q >> 2][0][q & 3][n][i] = chain;
;                     pg1 = tg1; pg2 = tg2; pv1 = tv1; pv2 = tv2;
;                 }
;                 __builtin_amdgcn_sched_barrier(0);
;             }
	v_cndmask_b32_e64 v114, v153, v155, s[40:41]
	v_cndmask_b32_e64 v99, v121, v127, s[38:39]
	v_cndmask_b32_e64 v98, v125, v131, s[38:39]
	v_pk_fma_f32 v[114:115], v[138:139], v[114:115], v[188:189]
	v_pk_fma_f32 v[98:99], v[136:137], v[98:99], v[114:115]
	v_pk_fma_f32 v[98:99], v[182:183], v[190:191], v[98:99]
	v_mul_f32_e32 v111, 0xbfb8aa3b, v99
	v_exp_f32_e32 v111, v111
	s_nop 0
	v_add_f32_e32 v111, 1.0, v111
	v_rcp_f32_e32 v111, v111
	s_nop 0
	v_mul_f32_e32 v99, v99, v111
	v_mul_f32_e32 v190, v98, v99
	v_mov_b32_dpp v129, v193 row_ror:2 row_mask:0xf bank_mask:0xf
	v_mov_b32_dpp v153, v192 row_ror:2 row_mask:0xf bank_mask:0xf
	v_mov_b32_dpp v127, v193 row_ror:1 row_mask:0xf bank_mask:0xf
	v_mov_b32_dpp v131, v192 row_ror:1 row_mask:0xf bank_mask:0xf
	v_cndmask_b32_e64 v115, v123, v129, s[40:41]
	v_cndmask_b32_e64 v114, v155, v153, s[40:41]
	v_cndmask_b32_e64 v99, v127, v121, s[38:39]
	v_cndmask_b32_e64 v98, v131, v125, s[38:39]
	v_pk_fma_f32 v[114:115], v[138:139], v[114:115], v[188:189]
	v_pk_fma_f32 v[98:99], v[136:137], v[98:99], v[114:115]
	v_pk_fma_f32 v[98:99], v[182:183], v[192:193], v[98:99]
	v_mul_f32_e32 v111, 0xbfb8aa3b, v99
	v_exp_f32_e32 v111, v111
	s_nop 0
	v_add_f32_e32 v111, 1.0, v111
	v_rcp_f32_e32 v111, v111
	s_nop 0
	v_mul_f32_e32 v99, v99, v111
	v_mul_f32_e32 v191, v98, v99
	v_mov_b32_dpp v123, v133 row_ror:2 row_mask:0xf bank_mask:0xf
	v_mov_b32_dpp v155, v132 row_ror:2 row_mask:0xf bank_mask:0xf
	v_mov_b32_dpp v121, v133 row_ror:1 row_mask:0xf bank_mask:0xf
	v_mov_b32_dpp v125, v132 row_ror:1 row_mask:0xf bank_mask:0xf
	v_cndmask_b32_e64 v115, v129, v123, s[40:41]
	v_cndmask_b32_e64 v114, v153, v155, s[40:41]
	v_cndmask_b32_e64 v99, v121, v127, s[38:39]
	v_cndmask_b32_e64 v98, v125, v131, s[38:39]
	v_pk_fma_f32 v[114:115], v[138:139], v[114:115], v[188:189]
	v_pk_fma_f32 v[98:99], v[136:137], v[98:99], v[114:115]
	v_pk_fma_f32 v[98:99], v[182:183], v[132:133], v[98:99]
	v_mul_f32_e32 v111, 0xbfb8aa3b, v99
	v_exp_f32_e32 v111, v111
	s_nop 0
	v_add_f32_e32 v111, 1.0, v111
	v_rcp_f32_e32 v111, v111
	s_nop 0
	v_mul_f32_e32 v99, v99, v111
	v_mul_f32_e32 v192, v98, v99
	v_mov_b32_dpp v114, v135 row_ror:1 row_mask:0xf bank_mask:0xf
	v_mov_b32_dpp v115, v135 row_ror:2 row_mask:0xf bank_mask:0xf
	v_mov_b32_dpp v129, v134 row_ror:2 row_mask:0xf bank_mask:0xf
	v_mov_b32_dpp v127, v134 row_ror:1 row_mask:0xf bank_mask:0xf
	v_cndmask_b32_e64 v99, v114, v121, s[38:39]
	v_cndmask_b32_e64 v115, v123, v115, s[40:41]
	v_cndmask_b32_e64 v114, v155, v129, s[40:41]
	v_cndmask_b32_e64 v98, v127, v125, s[38:39]
	v_pk_fma_f32 v[114:115], v[138:139], v[114:115], v[188:189]
	s_nop 0
	v_pk_fma_f32 v[98:99], v[136:137], v[98:99], v[114:115]
	s_nop 0
	v_pk_fma_f32 v[98:99], v[182:183], v[134:135], v[98:99]
	s_nop 0
	v_mul_f32_e32 v111, 0xbfb8aa3b, v99
	v_exp_f32_e32 v111, v111
	s_nop 0
	v_add_f32_e32 v111, 1.0, v111
	v_rcp_f32_e32 v111, v111
	s_nop 0
	v_mul_f32_e32 v99, v99, v111
	v_mul_f32_e32 v136, v98, v99
	global_load_dword v115, v[6:7], off offset:4
	global_load_dword v99, v[8:9], off offset:2052
	global_load_dword v98, v[10:11], off offset:4
	global_load_dword v133, v[16:17], off offset:4
	global_load_dword v132, v[20:21], off offset:3076
	global_load_dword v114, v[18:19], off offset:3076
	global_load_dword v139, v[22:23], off offset:1028
	global_load_dword v138, v[24:25], off offset:3076
	v_mov_b32_dpp v111, v176 row_ror:1 row_mask:0xf bank_mask:0xf
	v_mov_b32_dpp v121, v176 row_ror:2 row_mask:0xf bank_mask:0xf
	v_cndmask_b32_e64 v177, v111, 0, s[38:39]
	v_cndmask_b32_e64 v134, 0, v121, s[40:41]
	v_mov_b32_dpp v123, v178 row_ror:1 row_mask:0xf bank_mask:0xf
	v_cndmask_b32_e64 v179, v123, 0, s[38:39]
	v_mov_b32_dpp v125, v178 row_ror:2 row_mask:0xf bank_mask:0xf
	v_cndmask_b32_e64 v137, 0, v125, s[40:41]
	s_waitcnt vmcnt(4)
	v_fma_f32 v155, v115, v134, v133
	v_pk_mul_f32 v[134:135], v[98:99], v[176:177]
	s_waitcnt vmcnt(2)
	v_fma_f32 v137, v114, v137, v132
	v_add_f32_e32 v135, v135, v155
	v_add_f32_e32 v155, v134, v135
	v_mul_f32_e32 v134, 0xbfb8aa3b, v155
	v_exp_f32_e32 v159, v134
	v_mov_b32_e32 v135, v98
	s_waitcnt vmcnt(0)
	v_pk_mul_f32 v[176:177], v[138:139], v[178:179]
	v_mov_b32_e32 v134, v138
	v_add_f32_e32 v98, 1.0, v159
	v_rcp_f32_e32 v138, v98
	v_add_f32_e32 v137, v177, v137
	v_add_f32_e32 v137, v176, v137
	v_mov_b32_e32 v98, v139
	v_mul_f32_e32 v138, v155, v138
	v_mul_f32_e32 v137, v137, v138
	v_mov_b32_dpp v129, v181 row_ror:2 row_mask:0xf bank_mask:0xf
	v_mov_b32_dpp v153, v180 row_ror:2 row_mask:0xf bank_mask:0xf
	v_mov_b32_dpp v127, v181 row_ror:1 row_mask:0xf bank_mask:0xf
	v_mov_b32_dpp v131, v180 row_ror:1 row_mask:0xf bank_mask:0xf
	v_cndmask_b32_e64 v177, v121, v129, s[40:41]
	v_cndmask_b32_e64 v176, v125, v153, s[40:41]
	v_cndmask_b32_e64 v139, v127, v111, s[38:39]
	v_cndmask_b32_e64 v138, v131, v123, s[38:39]
	v_pk_fma_f32 v[176:177], v[114:115], v[176:177], v[132:133]
	v_pk_fma_f32 v[138:139], v[98:99], v[138:139], v[176:177]
	v_pk_fma_f32 v[138:139], v[134:135], v[180:181], v[138:139]
	v_mul_f32_e32 v111, 0xbfb8aa3b, v139
	v_exp_f32_e32 v111, v111
	s_nop 0
	v_add_f32_e32 v111, 1.0, v111
	v_rcp_f32_e32 v111, v111
	s_nop 0
	v_mul_f32_e32 v111, v139, v111
	v_mul_f32_e32 v138, v138, v111
	v_mov_b32_dpp v123, v107 row_ror:2 row_mask:0xf bank_mask:0xf
	v_mov_b32_dpp v155, v106 row_ror:2 row_mask:0xf bank_mask:0xf
	v_mov_b32_dpp v121, v107 row_ror:1 row_mask:0xf bank_mask:0xf
	v_mov_b32_dpp v125, v106 row_ror:1 row_mask:0xf bank_mask:0xf
	v_cndmask_b32_e64 v179, v129, v123, s[40:41]
	v_cndmask_b32_e64 v178, v153, v155, s[40:41]
	v_cndmask_b32_e64 v177, v121, v127, s[38:39]
	v_cndmask_b32_e64 v176, v125, v131, s[38:39]
; __device__ __forceinline__ float sigmoidf_(float x) { return __builtin_amdgcn_rcpf(1.0f + __expf(-x)); }
; template <int N> __device__ __forceinline__ float dpp_ror(float v) { return __builtin_bit_cast(float, __builtin_amdgcn_update_dpp(0, __builtin_bit_cast(int, v), 0x120 + N, 0xf, 0xf, false)); }
;     __device__ __forceinline__ void operator()(Acc& acc, const Unit& u, int wr, int wc, int fr, int fq) const {
;     ...
;         for (int n = 0; n < 2; ++n) {
; #pragma unroll
;             for (int i = 0; i < 4; ++i) {
;                 const int cg_ = ch0 + 4 * n + i, cv_ = DFF + cg_;
;                 const float g0 = cw[cg_], g1 = cw[NUP + cg_], g2 = cw[2 * NUP + cg_], gb = cb[cg_];
;                 const float v0 = cw[cv_], v1 = cw[NUP + cv_], v2 = cw[2 * NUP + cv_], vb = cb[cv_];
;                 float pg1 = 0.f, pg2 = 0.f, pv1 = 0.f, pv2 = 0.f;
; #pragma unroll
;                 for (int q = 0; q < 8; ++q) {
;                     float cgv = acc[q >> 2][0][q & 3][n][i], cvv = acc[q >> 2][1][q & 3][n][i];
;                     asm volatile("" : "+v"(cgv), "+v"(cvv) : "v"(chain));
;                     const float tg1 = dpp_ror<1>(cgv), tg2 = dpp_ror<2>(cgv), tv1 = dpp_ror<1>(cvv), tv2 = dpp_ror<2>(cvv);
;                     const float sg1 = fr >= 1 ? tg1 : pg1, sg2 = fr >= 2 ? tg2 : pg2, sv1 = fr >= 1 ? tv1 : pv1, sv2 = fr >= 2 ? tv2 : pv2;
;                     const float gg = gb + g0 * sg2 + g1 * sg1 + g2 * cgv;
;                     const float vv = vb + v0 * sv2 + v1 * sv1 + v2 * cvv;
;                     chain = gg * sigmoidf_(gg) * vv; acc[q >> 2][0][q & 3][n][i] = chain;
;                     pg1 = tg1; pg2 = tg2; pv1 = tv1; pv2 = tv2;
;                 }
;                 __builtin_amdgcn_sched_barrier(0);
;             }
	v_pk_fma_f32 v[178:179], v[114:115], v[178:179], v[132:133]
	v_pk_fma_f32 v[176:177], v[98:99], v[176:177], v[178:179]
	v_pk_fma_f32 v[106:107], v[134:135], v[106:107], v[176:177]
	v_mul_f32_e32 v111, 0xbfb8aa3b, v107
	v_exp_f32_e32 v111, v111
	s_nop 0
	v_add_f32_e32 v111, 1.0, v111
	v_rcp_f32_e32 v111, v111
	s_nop 0
	v_mul_f32_e32 v107, v107, v111
	v_mul_f32_e32 v106, v106, v107
	v_mov_b32_dpp v129, v91 row_ror:2 row_mask:0xf bank_mask:0xf
	v_mov_b32_dpp v139, v90 row_ror:2 row_mask:0xf bank_mask:0xf
	v_mov_b32_dpp v127, v91 row_ror:1 row_mask:0xf bank_mask:0xf
	v_mov_b32_dpp v131, v90 row_ror:1 row_mask:0xf bank_mask:0xf
	v_cndmask_b32_e64 v179, v123, v129, s[40:41]
	v_cndmask_b32_e64 v178, v155, v139, s[40:41]
	v_cndmask_b32_e64 v177, v127, v121, s[38:39]
	v_cndmask_b32_e64 v176, v131, v125, s[38:39]
	v_pk_fma_f32 v[178:179], v[114:115], v[178:179], v[132:133]
	v_pk_fma_f32 v[176:177], v[98:99], v[176:177], v[178:179]
	v_pk_fma_f32 v[90:91], v[134:135], v[90:91], v[176:177]
	v_mul_f32_e32 v107, 0xbfb8aa3b, v91
	v_exp_f32_e32 v107, v107
	s_nop 0
	v_add_f32_e32 v107, 1.0, v107
	v_rcp_f32_e32 v107, v107
	s_nop 0
	v_mul_f32_e32 v91, v91, v107
	v_mul_f32_e32 v90, v90, v91
	v_mov_b32_dpp v121, v75 row_ror:2 row_mask:0xf bank_mask:0xf
	v_mov_b32_dpp v125, v74 row_ror:2 row_mask:0xf bank_mask:0xf
	v_mov_b32_dpp v111, v75 row_ror:1 row_mask:0xf bank_mask:0xf
	v_mov_b32_dpp v123, v74 row_ror:1 row_mask:0xf bank_mask:0xf
	v_cndmask_b32_e64 v179, v129, v121, s[40:41]
	v_cndmask_b32_e64 v178, v139, v125, s[40:41]
	v_cndmask_b32_e64 v177, v111, v127, s[38:39]
	v_cndmask_b32_e64 v176, v123, v131, s[38:39]
	v_pk_fma_f32 v[178:179], v[114:115], v[178:179], v[132:133]
	v_pk_fma_f32 v[176:177], v[98:99], v[176:177], v[178:179]
	v_pk_fma_f32 v[74:75], v[134:135], v[74:75], v[176:177]
	v_mul_f32_e32 v91, 0xbfb8aa3b, v75
	v_exp_f32_e32 v91, v91
	s_nop 0
	v_add_f32_e32 v91, 1.0, v91
	v_rcp_f32_e32 v91, v91
	s_nop 0
	v_mul_f32_e32 v75, v75, v91
	v_mul_f32_e32 v91, v74, v75
	v_mov_b32_dpp v129, v59 row_ror:2 row_mask:0xf bank_mask:0xf
	v_mov_b32_dpp v139, v58 row_ror:2 row_mask:0xf bank_mask:0xf
	v_mov_b32_dpp v127, v59 row_ror:1 row_mask:0xf bank_mask:0xf
	v_mov_b32_dpp v131, v58 row_ror:1 row_mask:0xf bank_mask:0xf
	v_cndmask_b32_e64 v177, v121, v129, s[40:41]
	v_cndmask_b32_e64 v176, v125, v139, s[40:41]
	v_cndmask_b32_e64 v75, v127, v111, s[38:39]
	v_cndmask_b32_e64 v74, v131, v123, s[38:39]
	v_pk_fma_f32 v[176:177], v[114:115], v[176:177], v[132:133]
	v_pk_fma_f32 v[74:75], v[98:99], v[74:75], v[176:177]
	v_pk_fma_f32 v[58:59], v[134:135], v[58:59], v[74:75]
	v_mul_f32_e32 v74, 0xbfb8aa3b, v59
	v_exp_f32_e32 v74, v74
	s_nop 0
	v_add_f32_e32 v74, 1.0, v74
	v_rcp_f32_e32 v74, v74
	s_nop 0
	v_mul_f32_e32 v59, v59, v74
	v_mul_f32_e32 v107, v58, v59
	v_mov_b32_dpp v121, v63 row_ror:2 row_mask:0xf bank_mask:0xf
	v_mov_b32_dpp v125, v62 row_ror:2 row_mask:0xf bank_mask:0xf
	v_mov_b32_dpp v111, v63 row_ror:1 row_mask:0xf bank_mask:0xf
	v_mov_b32_dpp v123, v62 row_ror:1 row_mask:0xf bank_mask:0xf
	v_cndmask_b32_e64 v75, v129, v121, s[40:41]
	v_cndmask_b32_e64 v74, v139, v125, s[40:41]
	v_cndmask_b32_e64 v59, v111, v127, s[38:39]
	v_cndmask_b32_e64 v58, v123, v131, s[38:39]
	v_pk_fma_f32 v[74:75], v[114:115], v[74:75], v[132:133]
	v_pk_fma_f32 v[58:59], v[98:99], v[58:59], v[74:75]
	v_pk_fma_f32 v[58:59], v[134:135], v[62:63], v[58:59]
	v_mul_f32_e32 v62, 0xbfb8aa3b, v59
	v_exp_f32_e32 v62, v62
	s_nop 0
	v_add_f32_e32 v62, 1.0, v62
	v_rcp_f32_e32 v62, v62
	s_nop 0
	v_mul_f32_e32 v59, v59, v62
	v_mul_f32_e32 v139, v58, v59
	v_mov_b32_dpp v63, v83 row_ror:1 row_mask:0xf bank_mask:0xf
	v_mov_b32_dpp v74, v83 row_ror:2 row_mask:0xf bank_mask:0xf
	v_mov_b32_dpp v127, v82 row_ror:2 row_mask:0xf bank_mask:0xf
	v_mov_b32_dpp v75, v82 row_ror:1 row_mask:0xf bank_mask:0xf
	v_cndmask_b32_e64 v59, v63, v111, s[38:39]
	v_cndmask_b32_e64 v63, v121, v74, s[40:41]
	v_cndmask_b32_e64 v62, v125, v127, s[40:41]
	v_cndmask_b32_e64 v58, v75, v123, s[38:39]
	v_pk_fma_f32 v[62:63], v[114:115], v[62:63], v[132:133]
	s_nop 0
	v_pk_fma_f32 v[58:59], v[98:99], v[58:59], v[62:63]
	s_nop 0
	v_pk_fma_f32 v[58:59], v[134:135], v[82:83], v[58:59]
	s_nop 0
	v_mul_f32_e32 v62, 0xbfb8aa3b, v59
	v_exp_f32_e32 v62, v62
	s_nop 0
	v_add_f32_e32 v62, 1.0, v62
	v_rcp_f32_e32 v62, v62
	s_nop 0
	v_mul_f32_e32 v59, v59, v62
	v_mul_f32_e32 v98, v58, v59
	global_load_dword v63, v[6:7], off offset:8
	global_load_dword v59, v[8:9], off offset:2056
	global_load_dword v58, v[10:11], off offset:8
	global_load_dword v75, v[16:17], off offset:8
	global_load_dword v74, v[20:21], off offset:3080
	global_load_dword v62, v[18:19], off offset:3080
	global_load_dword v115, v[22:23], off offset:1032
	global_load_dword v114, v[24:25], off offset:3080
	v_mov_b32_dpp v111, v160 row_ror:1 row_mask:0xf bank_mask:0xf
	v_mov_b32_dpp v121, v160 row_ror:2 row_mask:0xf bank_mask:0xf
	v_cndmask_b32_e64 v161, v111, 0, s[38:39]
	v_cndmask_b32_e64 v82, 0, v121, s[40:41]
	v_mov_b32_dpp v123, v162 row_ror:1 row_mask:0xf bank_mask:0xf
	v_cndmask_b32_e64 v163, v123, 0, s[38:39]
	v_mov_b32_dpp v125, v162 row_ror:2 row_mask:0xf bank_mask:0xf
	v_cndmask_b32_e64 v99, 0, v125, s[40:41]
	s_waitcnt vmcnt(4)
	v_fma_f32 v132, v63, v82, v75
	v_pk_mul_f32 v[82:83], v[58:59], v[160:161]
	s_waitcnt vmcnt(2)
	v_fma_f32 v99, v62, v99, v74
	v_add_f32_e32 v83, v83, v132
	v_add_f32_e32 v135, v82, v83
	v_mul_f32_e32 v82, 0xbfb8aa3b, v135
	v_exp_f32_e32 v153, v82
	v_mov_b32_e32 v83, v58
	s_waitcnt vmcnt(0)
; __device__ __forceinline__ float sigmoidf_(float x) { return __builtin_amdgcn_rcpf(1.0f + __expf(-x)); }
; template <int N> __device__ __forceinline__ float dpp_ror(float v) { return __builtin_bit_cast(float, __builtin_amdgcn_update_dpp(0, __builtin_bit_cast(int, v), 0x120 + N, 0xf, 0xf, false)); }
;     __device__ __forceinline__ void operator()(Acc& acc, const Unit& u, int wr, int wc, int fr, int fq) const {
;     ...
;         for (int n = 0; n < 2; ++n) {
; #pragma unroll
;             for (int i = 0; i < 4; ++i) {
;                 const int cg_ = ch0 + 4 * n + i, cv_ = DFF + cg_;
;                 const float g0 = cw[cg_], g1 = cw[NUP + cg_], g2 = cw[2 * NUP + cg_], gb = cb[cg_];
;                 const float v0 = cw[cv_], v1 = cw[NUP + cv_], v2 = cw[2 * NUP + cv_], vb = cb[cv_];
;                 float pg1 = 0.f, pg2 = 0.f, pv1 = 0.f, pv2 = 0.f;
; #pragma unroll
;                 for (int q = 0; q < 8; ++q) {
;                     float cgv = acc[q >> 2][0][q & 3][n][i], cvv = acc[q >> 2][1][q & 3][n][i];
;                     asm volatile("" : "+v"(cgv), "+v"(cvv) : "v"(chain));
;                     const float tg1 = dpp_ror<1>(cgv), tg2 = dpp_ror<2>(cgv), tv1 = dpp_ror<1>(cvv), tv2 = dpp_ror<2>(cvv);
;                     const float sg1 = fr >= 1 ? tg1 : pg1, sg2 = fr >= 2 ? tg2 : pg2, sv1 = fr >= 1 ? tv1 : pv1, sv2 = fr >= 2 ? tv2 : pv2;
;                     const float gg = gb + g0 * sg2 + g1 * sg1 + g2 * cgv;
;                     const float vv = vb + v0 * sv2 + v1 * sv1 + v2 * cvv;
;                     chain = gg * sigmoidf_(gg) * vv; acc[q >> 2][0][q & 3][n][i] = chain;
;                     pg1 = tg1; pg2 = tg2; pv1 = tv1; pv2 = tv2;
;                 }
;                 __builtin_amdgcn_sched_barrier(0);
;             }
	v_pk_mul_f32 v[132:133], v[114:115], v[162:163]
	v_mov_b32_e32 v82, v114
	v_add_f32_e32 v58, 1.0, v153
	v_rcp_f32_e32 v114, v58
	v_add_f32_e32 v99, v133, v99
	v_add_f32_e32 v99, v132, v99
	v_mov_b32_e32 v58, v115
	v_mul_f32_e32 v114, v135, v114
	v_mul_f32_e32 v99, v99, v114
	v_mov_b32_dpp v129, v175 row_ror:2 row_mask:0xf bank_mask:0xf
	v_mov_b32_dpp v134, v174 row_ror:2 row_mask:0xf bank_mask:0xf
	v_mov_b32_dpp v127, v175 row_ror:1 row_mask:0xf bank_mask:0xf
	v_mov_b32_dpp v131, v174 row_ror:1 row_mask:0xf bank_mask:0xf
	v_cndmask_b32_e64 v133, v121, v129, s[40:41]
	v_cndmask_b32_e64 v132, v125, v134, s[40:41]
	v_cndmask_b32_e64 v115, v127, v111, s[38:39]
	v_cndmask_b32_e64 v114, v131, v123, s[38:39]
	v_pk_fma_f32 v[132:133], v[62:63], v[132:133], v[74:75]
	v_pk_fma_f32 v[114:115], v[58:59], v[114:115], v[132:133]
	v_pk_fma_f32 v[114:115], v[82:83], v[174:175], v[114:115]
	v_mul_f32_e32 v111, 0xbfb8aa3b, v115
	v_exp_f32_e32 v111, v111
	s_nop 0
	v_add_f32_e32 v111, 1.0, v111
	v_rcp_f32_e32 v111, v111
	s_nop 0
	v_mul_f32_e32 v111, v115, v111
	v_mul_f32_e32 v114, v114, v111
	v_mov_b32_dpp v123, v105 row_ror:2 row_mask:0xf bank_mask:0xf
	v_mov_b32_dpp v153, v104 row_ror:2 row_mask:0xf bank_mask:0xf
	v_mov_b32_dpp v121, v105 row_ror:1 row_mask:0xf bank_mask:0xf
	v_mov_b32_dpp v125, v104 row_ror:1 row_mask:0xf bank_mask:0xf
	v_cndmask_b32_e64 v135, v129, v123, s[40:41]
	v_cndmask_b32_e64 v134, v134, v153, s[40:41]
	v_cndmask_b32_e64 v133, v121, v127, s[38:39]
	v_cndmask_b32_e64 v132, v125, v131, s[38:39]
	v_pk_fma_f32 v[134:135], v[62:63], v[134:135], v[74:75]
	v_pk_fma_f32 v[132:133], v[58:59], v[132:133], v[134:135]
	v_pk_fma_f32 v[104:105], v[82:83], v[104:105], v[132:133]
	v_mul_f32_e32 v111, 0xbfb8aa3b, v105
	v_exp_f32_e32 v111, v111
	s_nop 0
	v_add_f32_e32 v111, 1.0, v111
	v_rcp_f32_e32 v111, v111
	s_nop 0
	v_mul_f32_e32 v105, v105, v111
	v_mul_f32_e32 v104, v104, v105
	v_mov_b32_dpp v127, v89 row_ror:2 row_mask:0xf bank_mask:0xf
	v_mov_b32_dpp v131, v88 row_ror:2 row_mask:0xf bank_mask:0xf
	v_mov_b32_dpp v115, v89 row_ror:1 row_mask:0xf bank_mask:0xf
	v_mov_b32_dpp v129, v88 row_ror:1 row_mask:0xf bank_mask:0xf
	v_cndmask_b32_e64 v135, v123, v127, s[40:41]
	v_cndmask_b32_e64 v134, v153, v131, s[40:41]
	v_cndmask_b32_e64 v133, v115, v121, s[38:39]
	v_cndmask_b32_e64 v132, v129, v125, s[38:39]
	v_pk_fma_f32 v[134:135], v[62:63], v[134:135], v[74:75]
	v_pk_fma_f32 v[132:133], v[58:59], v[132:133], v[134:135]
	v_pk_fma_f32 v[88:89], v[82:83], v[88:89], v[132:133]
	v_mul_f32_e32 v105, 0xbfb8aa3b, v89
	v_exp_f32_e32 v105, v105
	s_nop 0
	v_add_f32_e32 v105, 1.0, v105
	v_rcp_f32_e32 v105, v105
	s_nop 0
	v_mul_f32_e32 v89, v89, v105
	v_mul_f32_e32 v88, v88, v89
	v_mov_b32_dpp v121, v73 row_ror:2 row_mask:0xf bank_mask:0xf
	v_mov_b32_dpp v125, v72 row_ror:2 row_mask:0xf bank_mask:0xf
	v_mov_b32_dpp v111, v73 row_ror:1 row_mask:0xf bank_mask:0xf
	v_mov_b32_dpp v123, v72 row_ror:1 row_mask:0xf bank_mask:0xf
	v_cndmask_b32_e64 v135, v127, v121, s[40:41]
	v_cndmask_b32_e64 v134, v131, v125, s[40:41]
	v_cndmask_b32_e64 v133, v111, v115, s[38:39]
	v_cndmask_b32_e64 v132, v123, v129, s[38:39]
	v_pk_fma_f32 v[134:135], v[62:63], v[134:135], v[74:75]
	v_pk_fma_f32 v[132:133], v[58:59], v[132:133], v[134:135]
	v_pk_fma_f32 v[72:73], v[82:83], v[72:73], v[132:133]
	v_mul_f32_e32 v89, 0xbfb8aa3b, v73
	v_exp_f32_e32 v89, v89
	s_nop 0
	v_add_f32_e32 v89, 1.0, v89
	v_rcp_f32_e32 v89, v89
	s_nop 0
	v_mul_f32_e32 v73, v73, v89
	v_mul_f32_e32 v72, v72, v73
	v_mov_b32_dpp v115, v57 row_ror:2 row_mask:0xf bank_mask:0xf
	v_mov_b32_dpp v129, v56 row_ror:2 row_mask:0xf bank_mask:0xf
	v_mov_b32_dpp v105, v57 row_ror:1 row_mask:0xf bank_mask:0xf
	v_mov_b32_dpp v127, v56 row_ror:1 row_mask:0xf bank_mask:0xf
	v_cndmask_b32_e64 v135, v121, v115, s[40:41]
	v_cndmask_b32_e64 v134, v125, v129, s[40:41]
	v_cndmask_b32_e64 v133, v105, v111, s[38:39]
	v_cndmask_b32_e64 v132, v127, v123, s[38:39]
	v_pk_fma_f32 v[134:135], v[62:63], v[134:135], v[74:75]
	v_pk_fma_f32 v[132:133], v[58:59], v[132:133], v[134:135]
	v_pk_fma_f32 v[56:57], v[82:83], v[56:57], v[132:133]
	v_mul_f32_e32 v73, 0xbfb8aa3b, v57
	v_exp_f32_e32 v73, v73
	s_nop 0
	v_add_f32_e32 v73, 1.0, v73
	v_rcp_f32_e32 v73, v73
	s_nop 0
	v_mul_f32_e32 v57, v57, v73
	v_mul_f32_e32 v73, v56, v57
	v_mov_b32_dpp v121, v43 row_ror:2 row_mask:0xf bank_mask:0xf
	v_mov_b32_dpp v125, v42 row_ror:2 row_mask:0xf bank_mask:0xf
	v_mov_b32_dpp v111, v43 row_ror:1 row_mask:0xf bank_mask:0xf
	v_mov_b32_dpp v123, v42 row_ror:1 row_mask:0xf bank_mask:0xf
	v_cndmask_b32_e64 v133, v115, v121, s[40:41]
	v_cndmask_b32_e64 v132, v129, v125, s[40:41]
	v_cndmask_b32_e64 v57, v111, v105, s[38:39]
	v_cndmask_b32_e64 v56, v123, v127, s[38:39]
	v_pk_fma_f32 v[132:133], v[62:63], v[132:133], v[74:75]
	v_pk_fma_f32 v[56:57], v[58:59], v[56:57], v[132:133]
	v_pk_fma_f32 v[42:43], v[82:83], v[42:43], v[56:57]
	v_mul_f32_e32 v56, 0xbfb8aa3b, v43
	v_exp_f32_e32 v56, v56
	s_nop 0
	v_add_f32_e32 v56, 1.0, v56
	v_rcp_f32_e32 v56, v56
	s_nop 0
	v_mul_f32_e32 v43, v43, v56
	v_mul_f32_e32 v89, v42, v43
	v_mov_b32_dpp v57, v51 row_ror:1 row_mask:0xf bank_mask:0xf
	v_mov_b32_dpp v105, v51 row_ror:2 row_mask:0xf bank_mask:0xf
	v_mov_b32_dpp v127, v50 row_ror:2 row_mask:0xf bank_mask:0xf
	v_mov_b32_dpp v115, v50 row_ror:1 row_mask:0xf bank_mask:0xf
	v_cndmask_b32_e64 v43, v57, v111, s[38:39]
	v_cndmask_b32_e64 v57, v121, v105, s[40:41]
	v_cndmask_b32_e64 v56, v125, v127, s[40:41]
	v_cndmask_b32_e64 v42, v115, v123, s[38:39]
	v_pk_fma_f32 v[56:57], v[62:63], v[56:57], v[74:75]
	s_nop 0
	v_pk_fma_f32 v[42:43], v[58:59], v[42:43], v[56:57]
	s_nop 0
	v_pk_fma_f32 v[42:43], v[82:83], v[50:51], v[42:43]
	s_nop 0
	v_mul_f32_e32 v50, 0xbfb8aa3b, v43
	v_exp_f32_e32 v50, v50
	s_nop 0
	v_add_f32_e32 v50, 1.0, v50
	v_rcp_f32_e32 v50, v50
	s_nop 0
	v_mul_f32_e32 v43, v43, v50
	v_mul_f32_e32 v62, v42, v43
	global_load_dword v51, v[6:7], off offset:12
	global_load_dword v43, v[8:9], off offset:2060
	global_load_dword v42, v[10:11], off offset:12
	global_load_dword v57, v[16:17], off offset:12
	global_load_dword v56, v[20:21], off offset:3084
	global_load_dword v50, v[18:19], off offset:3084
	global_load_dword v75, v[22:23], off offset:1036
	global_load_dword v74, v[24:25], off offset:3084
	v_mov_b32_dpp v105, v154 row_ror:1 row_mask:0xf bank_mask:0xf
	v_mov_b32_dpp v111, v154 row_ror:2 row_mask:0xf bank_mask:0xf
	v_cndmask_b32_e64 v155, v105, 0, s[38:39]
	v_cndmask_b32_e64 v58, 0, v111, s[40:41]
	v_mov_b32_dpp v115, v158 row_ror:1 row_mask:0xf bank_mask:0xf
	v_cndmask_b32_e64 v159, v115, 0, s[38:39]
	v_mov_b32_dpp v121, v158 row_ror:2 row_mask:0xf bank_mask:0xf
	v_cndmask_b32_e64 v63, 0, v121, s[40:41]
	s_waitcnt vmcnt(4)
; __device__ __forceinline__ float sigmoidf_(float x) { return __builtin_amdgcn_rcpf(1.0f + __expf(-x)); }
; template <int N> __device__ __forceinline__ float dpp_ror(float v) { return __builtin_bit_cast(float, __builtin_amdgcn_update_dpp(0, __builtin_bit_cast(int, v), 0x120 + N, 0xf, 0xf, false)); }
;     __device__ __forceinline__ void operator()(Acc& acc, const Unit& u, int wr, int wc, int fr, int fq) const {
;     ...
;             for (int i = 0; i < 4; ++i) {
;                 const int cg_ = ch0 + 4 * n + i, cv_ = DFF + cg_;
;                 const float g0 = cw[cg_], g1 = cw[NUP + cg_], g2 = cw[2 * NUP + cg_], gb = cb[cg_];
;                 const float v0 = cw[cv_], v1 = cw[NUP + cv_], v2 = cw[2 * NUP + cv_], vb = cb[cv_];
;                 float pg1 = 0.f, pg2 = 0.f, pv1 = 0.f, pv2 = 0.f;
; #pragma unroll
;                 for (int q = 0; q < 8; ++q) {
;                     float cgv = acc[q >> 2][0][q & 3][n][i], cvv = acc[q >> 2][1][q & 3][n][i];
;                     asm volatile("" : "+v"(cgv), "+v"(cvv) : "v"(chain));
;                     const float tg1 = dpp_ror<1>(cgv), tg2 = dpp_ror<2>(cgv), tv1 = dpp_ror<1>(cvv), tv2 = dpp_ror<2>(cvv);
;                     const float sg1 = fr >= 1 ? tg1 : pg1, sg2 = fr >= 2 ? tg2 : pg2, sv1 = fr >= 1 ? tv1 : pv1, sv2 = fr >= 2 ? tv2 : pv2;
;                     const float gg = gb + g0 * sg2 + g1 * sg1 + g2 * cgv;
;                     const float vv = vb + v0 * sv2 + v1 * sv1 + v2 * cvv;
;                     chain = gg * sigmoidf_(gg) * vv; acc[q >> 2][0][q & 3][n][i] = chain;
;                     pg1 = tg1; pg2 = tg2; pv1 = tv1; pv2 = tv2;
;                 }
	v_fma_f32 v82, v51, v58, v57
	v_pk_mul_f32 v[58:59], v[42:43], v[154:155]
	s_waitcnt vmcnt(2)
	v_fma_f32 v63, v50, v63, v56
	v_add_f32_e32 v59, v59, v82
	v_add_f32_e32 v131, v58, v59
	v_mul_f32_e32 v58, 0xbfb8aa3b, v131
	v_exp_f32_e32 v132, v58
	v_mov_b32_e32 v59, v42
	s_waitcnt vmcnt(0)
	v_pk_mul_f32 v[82:83], v[74:75], v[158:159]
	v_mov_b32_e32 v58, v74
	v_add_f32_e32 v42, 1.0, v132
	v_rcp_f32_e32 v74, v42
	v_add_f32_e32 v63, v83, v63
	v_add_f32_e32 v63, v82, v63
	v_mov_b32_e32 v42, v75
	v_mul_f32_e32 v74, v131, v74
	v_mul_f32_e32 v63, v63, v74
	v_mov_b32_dpp v125, v157 row_ror:2 row_mask:0xf bank_mask:0xf
	v_mov_b32_dpp v129, v156 row_ror:2 row_mask:0xf bank_mask:0xf
	v_mov_b32_dpp v123, v157 row_ror:1 row_mask:0xf bank_mask:0xf
	v_mov_b32_dpp v127, v156 row_ror:1 row_mask:0xf bank_mask:0xf
	v_cndmask_b32_e64 v83, v111, v125, s[40:41]
	v_cndmask_b32_e64 v82, v121, v129, s[40:41]
	v_cndmask_b32_e64 v75, v123, v105, s[38:39]
	v_cndmask_b32_e64 v74, v127, v115, s[38:39]
	v_pk_fma_f32 v[82:83], v[50:51], v[82:83], v[56:57]
	v_pk_fma_f32 v[74:75], v[42:43], v[74:75], v[82:83]
	v_pk_fma_f32 v[74:75], v[58:59], v[156:157], v[74:75]
	v_mul_f32_e32 v82, 0xbfb8aa3b, v75
	v_exp_f32_e32 v82, v82
	s_nop 0
	v_add_f32_e32 v82, 1.0, v82
	v_rcp_f32_e32 v82, v82
	s_nop 0
	v_mul_f32_e32 v75, v75, v82
	v_mul_f32_e32 v74, v74, v75
	v_mov_b32_dpp v111, v103 row_ror:2 row_mask:0xf bank_mask:0xf
	v_mov_b32_dpp v121, v102 row_ror:2 row_mask:0xf bank_mask:0xf
	v_mov_b32_dpp v105, v103 row_ror:1 row_mask:0xf bank_mask:0xf
	v_mov_b32_dpp v115, v102 row_ror:1 row_mask:0xf bank_mask:0xf
	v_cndmask_b32_e64 v133, v125, v111, s[40:41]
	v_cndmask_b32_e64 v132, v129, v121, s[40:41]
	v_cndmask_b32_e64 v83, v105, v123, s[38:39]
	v_cndmask_b32_e64 v82, v115, v127, s[38:39]
	v_pk_fma_f32 v[132:133], v[50:51], v[132:133], v[56:57]
	v_pk_fma_f32 v[82:83], v[42:43], v[82:83], v[132:133]
	v_pk_fma_f32 v[82:83], v[58:59], v[102:103], v[82:83]
	v_mul_f32_e32 v75, 0xbfb8aa3b, v83
	v_exp_f32_e32 v75, v75
	s_nop 0
	v_add_f32_e32 v75, 1.0, v75
	v_rcp_f32_e32 v75, v75
	s_nop 0
	v_mul_f32_e32 v75, v83, v75
	v_mul_f32_e32 v75, v82, v75
	v_mov_b32_dpp v125, v87 row_ror:2 row_mask:0xf bank_mask:0xf
	v_mov_b32_dpp v129, v86 row_ror:2 row_mask:0xf bank_mask:0xf
	v_mov_b32_dpp v123, v87 row_ror:1 row_mask:0xf bank_mask:0xf
	v_mov_b32_dpp v127, v86 row_ror:1 row_mask:0xf bank_mask:0xf
	v_cndmask_b32_e64 v103, v111, v125, s[40:41]
	v_cndmask_b32_e64 v102, v121, v129, s[40:41]
	v_cndmask_b32_e64 v83, v123, v105, s[38:39]
	v_cndmask_b32_e64 v82, v127, v115, s[38:39]
	v_pk_fma_f32 v[102:103], v[50:51], v[102:103], v[56:57]
	v_pk_fma_f32 v[82:83], v[42:43], v[82:83], v[102:103]
	v_pk_fma_f32 v[82:83], v[58:59], v[86:87], v[82:83]
	v_mul_f32_e32 v86, 0xbfb8aa3b, v83
	v_exp_f32_e32 v86, v86
	s_nop 0
	v_add_f32_e32 v86, 1.0, v86
	v_rcp_f32_e32 v86, v86
	s_nop 0
	v_mul_f32_e32 v83, v83, v86
	v_mul_f32_e32 v82, v82, v83
	v_mov_b32_dpp v111, v71 row_ror:2 row_mask:0xf bank_mask:0xf
	v_mov_b32_dpp v121, v70 row_ror:2 row_mask:0xf bank_mask:0xf
	v_mov_b32_dpp v105, v71 row_ror:1 row_mask:0xf bank_mask:0xf
	v_mov_b32_dpp v115, v70 row_ror:1 row_mask:0xf bank_mask:0xf
	v_cndmask_b32_e64 v103, v125, v111, s[40:41]
	v_cndmask_b32_e64 v102, v129, v121, s[40:41]
	v_cndmask_b32_e64 v87, v105, v123, s[38:39]
	v_cndmask_b32_e64 v86, v115, v127, s[38:39]
	v_pk_fma_f32 v[102:103], v[50:51], v[102:103], v[56:57]
	v_pk_fma_f32 v[86:87], v[42:43], v[86:87], v[102:103]
	v_pk_fma_f32 v[70:71], v[58:59], v[70:71], v[86:87]
	v_mul_f32_e32 v83, 0xbfb8aa3b, v71
	v_exp_f32_e32 v83, v83
	s_nop 0
	v_add_f32_e32 v83, 1.0, v83
	v_rcp_f32_e32 v83, v83
	s_nop 0
	v_mul_f32_e32 v71, v71, v83
	v_mul_f32_e32 v70, v70, v71
	v_mov_b32_dpp v125, v55 row_ror:2 row_mask:0xf bank_mask:0xf
	v_mov_b32_dpp v129, v54 row_ror:2 row_mask:0xf bank_mask:0xf
	v_mov_b32_dpp v123, v55 row_ror:1 row_mask:0xf bank_mask:0xf
	v_mov_b32_dpp v127, v54 row_ror:1 row_mask:0xf bank_mask:0xf
	v_cndmask_b32_e64 v103, v111, v125, s[40:41]
	v_cndmask_b32_e64 v102, v121, v129, s[40:41]
	v_cndmask_b32_e64 v87, v123, v105, s[38:39]
	v_cndmask_b32_e64 v86, v127, v115, s[38:39]
	v_pk_fma_f32 v[102:103], v[50:51], v[102:103], v[56:57]
	v_pk_fma_f32 v[86:87], v[42:43], v[86:87], v[102:103]
	v_pk_fma_f32 v[54:55], v[58:59], v[54:55], v[86:87]
	v_mul_f32_e32 v71, 0xbfb8aa3b, v55
	v_exp_f32_e32 v71, v71
	s_nop 0
	v_add_f32_e32 v71, 1.0, v71
	v_rcp_f32_e32 v71, v71
	s_nop 0
	v_mul_f32_e32 v55, v55, v71
	v_mul_f32_e32 v55, v54, v55
	v_mov_b32_dpp v105, v39 row_ror:2 row_mask:0xf bank_mask:0xf
	v_mov_b32_dpp v115, v38 row_ror:2 row_mask:0xf bank_mask:0xf
	v_mov_b32_dpp v83, v39 row_ror:1 row_mask:0xf bank_mask:0xf
	v_mov_b32_dpp v111, v38 row_ror:1 row_mask:0xf bank_mask:0xf
	v_cndmask_b32_e64 v103, v125, v105, s[40:41]
	v_cndmask_b32_e64 v102, v129, v115, s[40:41]
	v_cndmask_b32_e64 v87, v83, v123, s[38:39]
	v_cndmask_b32_e64 v86, v111, v127, s[38:39]
	v_pk_fma_f32 v[102:103], v[50:51], v[102:103], v[56:57]
	s_nop 0
	v_pk_fma_f32 v[86:87], v[42:43], v[86:87], v[102:103]
	v_pk_fma_f32 v[38:39], v[58:59], v[38:39], v[86:87]
	v_mul_f32_e32 v54, 0xbfb8aa3b, v39
	v_exp_f32_e32 v54, v54
	s_nop 0
	v_add_f32_e32 v54, 1.0, v54
	v_rcp_f32_e32 v54, v54
	s_nop 0
	v_mul_f32_e32 v39, v39, v54
	v_mul_f32_e32 v71, v38, v39
	v_mov_b32_dpp v86, v41 row_ror:1 row_mask:0xf bank_mask:0xf
	v_mov_b32_dpp v87, v41 row_ror:2 row_mask:0xf bank_mask:0xf
	v_mov_b32_dpp v103, v40 row_ror:2 row_mask:0xf bank_mask:0xf
	v_mov_b32_dpp v102, v40 row_ror:1 row_mask:0xf bank_mask:0xf
	v_cndmask_b32_e64 v39, v86, v83, s[38:39]
	v_cndmask_b32_e64 v87, v105, v87, s[40:41]
	v_cndmask_b32_e64 v86, v115, v103, s[40:41]
	v_cndmask_b32_e64 v38, v102, v111, s[38:39]
	v_pk_fma_f32 v[50:51], v[50:51], v[86:87], v[56:57]
	s_nop 0
	v_pk_fma_f32 v[38:39], v[42:43], v[38:39], v[50:51]
	s_nop 0
	v_pk_fma_f32 v[38:39], v[58:59], v[40:41], v[38:39]
	s_nop 0
	v_mul_f32_e32 v40, 0xbfb8aa3b, v39
	v_exp_f32_e32 v40, v40
	s_nop 0
	v_add_f32_e32 v40, 1.0, v40
	v_rcp_f32_e32 v40, v40
	s_nop 0
	v_mul_f32_e32 v39, v39, v40
	v_mul_f32_e32 v54, v38, v39
	global_load_dword v41, v[6:7], off offset:16
	global_load_dword v39, v[8:9], off offset:2064
	global_load_dword v38, v[10:11], off offset:16
	global_load_dword v43, v[16:17], off offset:16
	global_load_dword v42, v[20:21], off offset:3088
	global_load_dword v40, v[18:19], off offset:3088
	global_load_dword v57, v[22:23], off offset:1040
	global_load_dword v56, v[24:25], off offset:3088
	v_mov_b32_dpp v83, v130 row_ror:1 row_mask:0xf bank_mask:0xf
	v_mov_b32_dpp v86, v130 row_ror:2 row_mask:0xf bank_mask:0xf
	v_cndmask_b32_e64 v131, v83, 0, s[38:39]
	v_cndmask_b32_e64 v50, 0, v86, s[40:41]
	v_mov_b32_dpp v87, v152 row_ror:1 row_mask:0xf bank_mask:0xf
	v_mov_b32_dpp v102, v152 row_ror:2 row_mask:0xf bank_mask:0xf
	v_cndmask_b32_e64 v153, v87, 0, s[38:39]
	v_cndmask_b32_e64 v58, 0, v102, s[40:41]
	s_waitcnt vmcnt(4)
; __device__ __forceinline__ float sigmoidf_(float x) { return __builtin_amdgcn_rcpf(1.0f + __expf(-x)); }
; template <int N> __device__ __forceinline__ float dpp_ror(float v) { return __builtin_bit_cast(float, __builtin_amdgcn_update_dpp(0, __builtin_bit_cast(int, v), 0x120 + N, 0xf, 0xf, false)); }
;     __device__ __forceinline__ void operator()(Acc& acc, const Unit& u, int wr, int wc, int fr, int fq) const {
;     ...
;             for (int i = 0; i < 4; ++i) {
;                 const int cg_ = ch0 + 4 * n + i, cv_ = DFF + cg_;
;                 const float g0 = cw[cg_], g1 = cw[NUP + cg_], g2 = cw[2 * NUP + cg_], gb = cb[cg_];
;                 const float v0 = cw[cv_], v1 = cw[NUP + cv_], v2 = cw[2 * NUP + cv_], vb = cb[cv_];
;                 float pg1 = 0.f, pg2 = 0.f, pv1 = 0.f, pv2 = 0.f;
; #pragma unroll
;                 for (int q = 0; q < 8; ++q) {
;                     float cgv = acc[q >> 2][0][q & 3][n][i], cvv = acc[q >> 2][1][q & 3][n][i];
;                     asm volatile("" : "+v"(cgv), "+v"(cvv) : "v"(chain));
;                     const float tg1 = dpp_ror<1>(cgv), tg2 = dpp_ror<2>(cgv), tv1 = dpp_ror<1>(cvv), tv2 = dpp_ror<2>(cvv);
;                     const float sg1 = fr >= 1 ? tg1 : pg1, sg2 = fr >= 2 ? tg2 : pg2, sv1 = fr >= 1 ? tv1 : pv1, sv2 = fr >= 2 ? tv2 : pv2;
;                     const float gg = gb + g0 * sg2 + g1 * sg1 + g2 * cgv;
;                     const float vv = vb + v0 * sv2 + v1 * sv1 + v2 * cvv;
;                     chain = gg * sigmoidf_(gg) * vv; acc[q >> 2][0][q & 3][n][i] = chain;
;                     pg1 = tg1; pg2 = tg2; pv1 = tv1; pv2 = tv2;
;                 }
	v_fma_f32 v59, v41, v50, v43
	v_pk_mul_f32 v[50:51], v[38:39], v[130:131]
	s_waitcnt vmcnt(2)
	v_fma_f32 v121, v40, v58, v42
	v_add_f32_e32 v51, v51, v59
	v_add_f32_e32 v123, v50, v51
	v_mul_f32_e32 v50, 0xbfb8aa3b, v123
	v_exp_f32_e32 v125, v50
	v_mov_b32_e32 v51, v38
	s_waitcnt vmcnt(0)
	v_pk_mul_f32 v[58:59], v[56:57], v[152:153]
	v_mov_b32_e32 v50, v56
	v_add_f32_e32 v38, 1.0, v125
	v_rcp_f32_e32 v56, v38
	v_mov_b32_e32 v38, v57
	v_add_f32_e32 v57, v59, v121
	v_add_f32_e32 v57, v58, v57
	v_mul_f32_e32 v56, v123, v56
	v_mul_f32_e32 v56, v57, v56
	v_mov_b32_dpp v105, v119 row_ror:2 row_mask:0xf bank_mask:0xf
	v_mov_b32_dpp v111, v118 row_ror:1 row_mask:0xf bank_mask:0xf
	v_mov_b32_dpp v115, v118 row_ror:2 row_mask:0xf bank_mask:0xf
	v_mov_b32_dpp v103, v119 row_ror:1 row_mask:0xf bank_mask:0xf
	v_cndmask_b32_e64 v58, v111, v87, s[38:39]
	v_cndmask_b32_e64 v87, v86, v105, s[40:41]
	v_cndmask_b32_e64 v86, v102, v115, s[40:41]
	v_cndmask_b32_e64 v59, v103, v83, s[38:39]
	v_pk_fma_f32 v[86:87], v[40:41], v[86:87], v[42:43]
	v_pk_fma_f32 v[58:59], v[38:39], v[58:59], v[86:87]
	v_pk_fma_f32 v[58:59], v[50:51], v[118:119], v[58:59]
	v_mul_f32_e32 v57, 0xbfb8aa3b, v59
	v_exp_f32_e32 v57, v57
	s_nop 0
	v_add_f32_e32 v57, 1.0, v57
	v_rcp_f32_e32 v57, v57
	s_nop 0
	v_mul_f32_e32 v57, v59, v57
	v_mul_f32_e32 v57, v58, v57
	v_mov_b32_dpp v102, v101 row_ror:2 row_mask:0xf bank_mask:0xf
	v_mov_b32_dpp v119, v100 row_ror:2 row_mask:0xf bank_mask:0xf
	v_mov_b32_dpp v83, v101 row_ror:1 row_mask:0xf bank_mask:0xf
	v_mov_b32_dpp v118, v100 row_ror:1 row_mask:0xf bank_mask:0xf
	v_cndmask_b32_e64 v87, v105, v102, s[40:41]
	v_cndmask_b32_e64 v86, v115, v119, s[40:41]
	v_cndmask_b32_e64 v59, v83, v103, s[38:39]
	v_cndmask_b32_e64 v58, v118, v111, s[38:39]
	v_pk_fma_f32 v[86:87], v[40:41], v[86:87], v[42:43]
	v_pk_fma_f32 v[58:59], v[38:39], v[58:59], v[86:87]
	v_pk_fma_f32 v[58:59], v[50:51], v[100:101], v[58:59]
	v_mul_f32_e32 v86, 0xbfb8aa3b, v59
	v_exp_f32_e32 v86, v86
	s_nop 0
	v_add_f32_e32 v86, 1.0, v86
	v_rcp_f32_e32 v86, v86
	s_nop 0
	v_mul_f32_e32 v59, v59, v86
	v_mul_f32_e32 v58, v58, v59
	v_mov_b32_dpp v105, v85 row_ror:2 row_mask:0xf bank_mask:0xf
	v_mov_b32_dpp v115, v84 row_ror:2 row_mask:0xf bank_mask:0xf
	v_mov_b32_dpp v103, v85 row_ror:1 row_mask:0xf bank_mask:0xf
	v_mov_b32_dpp v111, v84 row_ror:1 row_mask:0xf bank_mask:0xf
	v_cndmask_b32_e64 v101, v102, v105, s[40:41]
	v_cndmask_b32_e64 v100, v119, v115, s[40:41]
	v_cndmask_b32_e64 v87, v103, v83, s[38:39]
	v_cndmask_b32_e64 v86, v111, v118, s[38:39]
	v_pk_fma_f32 v[100:101], v[40:41], v[100:101], v[42:43]
	v_pk_fma_f32 v[86:87], v[38:39], v[86:87], v[100:101]
	v_pk_fma_f32 v[84:85], v[50:51], v[84:85], v[86:87]
	v_mul_f32_e32 v59, 0xbfb8aa3b, v85
	v_exp_f32_e32 v59, v59
	s_nop 0
	v_add_f32_e32 v59, 1.0, v59
	v_rcp_f32_e32 v59, v59
	s_nop 0
	v_mul_f32_e32 v59, v85, v59
	v_mul_f32_e32 v59, v84, v59
	v_mov_b32_dpp v100, v69 row_ror:2 row_mask:0xf bank_mask:0xf
	v_mov_b32_dpp v102, v68 row_ror:2 row_mask:0xf bank_mask:0xf
	v_mov_b32_dpp v83, v69 row_ror:1 row_mask:0xf bank_mask:0xf
	v_mov_b32_dpp v101, v68 row_ror:1 row_mask:0xf bank_mask:0xf
	v_cndmask_b32_e64 v87, v105, v100, s[40:41]
	v_cndmask_b32_e64 v86, v115, v102, s[40:41]
	v_cndmask_b32_e64 v85, v83, v103, s[38:39]
	v_cndmask_b32_e64 v84, v101, v111, s[38:39]
	v_pk_fma_f32 v[86:87], v[40:41], v[86:87], v[42:43]
	v_pk_fma_f32 v[84:85], v[38:39], v[84:85], v[86:87]
	v_pk_fma_f32 v[68:69], v[50:51], v[68:69], v[84:85]
	v_mul_f32_e32 v84, 0xbfb8aa3b, v69
	v_exp_f32_e32 v84, v84
	s_nop 0
	v_add_f32_e32 v84, 1.0, v84
	v_rcp_f32_e32 v84, v84
	s_nop 0
	v_mul_f32_e32 v69, v69, v84
	v_mul_f32_e32 v68, v68, v69
	v_mov_b32_dpp v105, v53 row_ror:2 row_mask:0xf bank_mask:0xf
	v_mov_b32_dpp v115, v52 row_ror:2 row_mask:0xf bank_mask:0xf
	v_mov_b32_dpp v103, v53 row_ror:1 row_mask:0xf bank_mask:0xf
	v_mov_b32_dpp v111, v52 row_ror:1 row_mask:0xf bank_mask:0xf
	v_cndmask_b32_e64 v87, v100, v105, s[40:41]
	v_cndmask_b32_e64 v86, v102, v115, s[40:41]
	v_cndmask_b32_e64 v85, v103, v83, s[38:39]
	v_cndmask_b32_e64 v84, v111, v101, s[38:39]
	v_pk_fma_f32 v[86:87], v[40:41], v[86:87], v[42:43]
	v_pk_fma_f32 v[84:85], v[38:39], v[84:85], v[86:87]
	v_pk_fma_f32 v[52:53], v[50:51], v[52:53], v[84:85]
	v_mul_f32_e32 v69, 0xbfb8aa3b, v53
	v_exp_f32_e32 v69, v69
	s_nop 0
	v_add_f32_e32 v69, 1.0, v69
	v_rcp_f32_e32 v69, v69
	s_nop 0
	v_mul_f32_e32 v53, v53, v69
	v_mul_f32_e32 v52, v52, v53
	v_mov_b32_dpp v100, v37 row_ror:2 row_mask:0xf bank_mask:0xf
	v_mov_b32_dpp v102, v36 row_ror:2 row_mask:0xf bank_mask:0xf
	v_mov_b32_dpp v83, v37 row_ror:1 row_mask:0xf bank_mask:0xf
	v_mov_b32_dpp v101, v36 row_ror:1 row_mask:0xf bank_mask:0xf
	v_cndmask_b32_e64 v87, v105, v100, s[40:41]
	v_cndmask_b32_e64 v86, v115, v102, s[40:41]
	v_cndmask_b32_e64 v85, v83, v103, s[38:39]
	v_cndmask_b32_e64 v84, v101, v111, s[38:39]
	v_pk_fma_f32 v[86:87], v[40:41], v[86:87], v[42:43]
	s_nop 0
	v_pk_fma_f32 v[84:85], v[38:39], v[84:85], v[86:87]
	v_pk_fma_f32 v[36:37], v[50:51], v[36:37], v[84:85]
	v_mul_f32_e32 v53, 0xbfb8aa3b, v37
	v_exp_f32_e32 v53, v53
	s_nop 0
	v_add_f32_e32 v53, 1.0, v53
	v_rcp_f32_e32 v53, v53
	s_nop 0
	v_mul_f32_e32 v37, v37, v53
	v_mul_f32_e32 v53, v36, v37
	v_mov_b32_dpp v84, v35 row_ror:2 row_mask:0xf bank_mask:0xf
	v_mov_b32_dpp v85, v34 row_ror:1 row_mask:0xf bank_mask:0xf
	v_mov_b32_dpp v86, v34 row_ror:2 row_mask:0xf bank_mask:0xf
	v_mov_b32_dpp v69, v35 row_ror:1 row_mask:0xf bank_mask:0xf
	v_cndmask_b32_e64 v36, v85, v101, s[38:39]
	v_cndmask_b32_e64 v85, v100, v84, s[40:41]
	v_cndmask_b32_e64 v84, v102, v86, s[40:41]
	v_cndmask_b32_e64 v37, v69, v83, s[38:39]
	v_pk_fma_f32 v[40:41], v[40:41], v[84:85], v[42:43]
	s_nop 0
	v_pk_fma_f32 v[36:37], v[38:39], v[36:37], v[40:41]
	s_nop 0
	v_pk_fma_f32 v[34:35], v[50:51], v[34:35], v[36:37]
	s_nop 0
	v_mul_f32_e32 v36, 0xbfb8aa3b, v35
	v_exp_f32_e32 v36, v36
	s_nop 0
	v_add_f32_e32 v36, 1.0, v36
	v_rcp_f32_e32 v36, v36
	s_nop 0
	v_mul_f32_e32 v35, v35, v36
	v_mul_f32_e32 v42, v34, v35
	global_load_dword v37, v[6:7], off offset:20
	global_load_dword v35, v[8:9], off offset:2068
	global_load_dword v34, v[10:11], off offset:20
	global_load_dword v39, v[16:17], off offset:20
	global_load_dword v38, v[20:21], off offset:3092
	global_load_dword v36, v[18:19], off offset:3092
	global_load_dword v51, v[22:23], off offset:1044
	global_load_dword v50, v[24:25], off offset:3092
	v_mov_b32_dpp v69, v126 row_ror:1 row_mask:0xf bank_mask:0xf
	v_mov_b32_dpp v83, v126 row_ror:2 row_mask:0xf bank_mask:0xf
	v_cndmask_b32_e64 v127, v69, 0, s[38:39]
	v_cndmask_b32_e64 v40, 0, v83, s[40:41]
	v_mov_b32_dpp v86, v128 row_ror:1 row_mask:0xf bank_mask:0xf
	v_cndmask_b32_e64 v129, v86, 0, s[38:39]
	v_mov_b32_dpp v87, v128 row_ror:2 row_mask:0xf bank_mask:0xf
	v_cndmask_b32_e64 v43, 0, v87, s[40:41]
	s_waitcnt vmcnt(4)
; __device__ __forceinline__ float sigmoidf_(float x) { return __builtin_amdgcn_rcpf(1.0f + __expf(-x)); }
; template <int N> __device__ __forceinline__ float dpp_ror(float v) { return __builtin_bit_cast(float, __builtin_amdgcn_update_dpp(0, __builtin_bit_cast(int, v), 0x120 + N, 0xf, 0xf, false)); }
;     __device__ __forceinline__ void operator()(Acc& acc, const Unit& u, int wr, int wc, int fr, int fq) const {
;     ...
;             for (int i = 0; i < 4; ++i) {
;                 const int cg_ = ch0 + 4 * n + i, cv_ = DFF + cg_;
;                 const float g0 = cw[cg_], g1 = cw[NUP + cg_], g2 = cw[2 * NUP + cg_], gb = cb[cg_];
;                 const float v0 = cw[cv_], v1 = cw[NUP + cv_], v2 = cw[2 * NUP + cv_], vb = cb[cv_];
;                 float pg1 = 0.f, pg2 = 0.f, pv1 = 0.f, pv2 = 0.f;
; #pragma unroll
;                 for (int q = 0; q < 8; ++q) {
;                     float cgv = acc[q >> 2][0][q & 3][n][i], cvv = acc[q >> 2][1][q & 3][n][i];
;                     asm volatile("" : "+v"(cgv), "+v"(cvv) : "v"(chain));
;                     const float tg1 = dpp_ror<1>(cgv), tg2 = dpp_ror<2>(cgv), tv1 = dpp_ror<1>(cvv), tv2 = dpp_ror<2>(cvv);
;                     const float sg1 = fr >= 1 ? tg1 : pg1, sg2 = fr >= 2 ? tg2 : pg2, sv1 = fr >= 1 ? tv1 : pv1, sv2 = fr >= 2 ? tv2 : pv2;
;                     const float gg = gb + g0 * sg2 + g1 * sg1 + g2 * cgv;
;                     const float vv = vb + v0 * sv2 + v1 * sv1 + v2 * cvv;
;                     chain = gg * sigmoidf_(gg) * vv; acc[q >> 2][0][q & 3][n][i] = chain;
;                     pg1 = tg1; pg2 = tg2; pv1 = tv1; pv2 = tv2;
;                 }
	v_fma_f32 v84, v37, v40, v39
	v_pk_mul_f32 v[40:41], v[34:35], v[126:127]
	s_waitcnt vmcnt(2)
	v_fma_f32 v43, v36, v43, v38
	v_add_f32_e32 v41, v41, v84
	v_add_f32_e32 v105, v40, v41
	v_mul_f32_e32 v40, 0xbfb8aa3b, v105
	v_exp_f32_e32 v111, v40
	v_mov_b32_e32 v41, v34
	s_waitcnt vmcnt(0)
	v_pk_mul_f32 v[84:85], v[50:51], v[128:129]
	v_mov_b32_e32 v40, v50
	v_add_f32_e32 v34, 1.0, v111
	v_rcp_f32_e32 v50, v34
	v_add_f32_e32 v43, v85, v43
	v_add_f32_e32 v43, v84, v43
	v_mov_b32_e32 v34, v51
	v_mul_f32_e32 v50, v105, v50
	v_mul_f32_e32 v43, v43, v50
	v_mov_b32_dpp v101, v117 row_ror:2 row_mask:0xf bank_mask:0xf
	v_mov_b32_dpp v103, v116 row_ror:2 row_mask:0xf bank_mask:0xf
	v_mov_b32_dpp v100, v117 row_ror:1 row_mask:0xf bank_mask:0xf
	v_mov_b32_dpp v102, v116 row_ror:1 row_mask:0xf bank_mask:0xf
	v_cndmask_b32_e64 v85, v83, v101, s[40:41]
	v_cndmask_b32_e64 v84, v87, v103, s[40:41]
	v_cndmask_b32_e64 v51, v100, v69, s[38:39]
	v_cndmask_b32_e64 v50, v102, v86, s[38:39]
	v_pk_fma_f32 v[84:85], v[36:37], v[84:85], v[38:39]
	v_pk_fma_f32 v[50:51], v[34:35], v[50:51], v[84:85]
	s_nop 0
	v_pk_fma_f32 v[50:51], v[40:41], v[116:117], v[50:51]
	s_nop 0
	v_mul_f32_e32 v69, 0xbfb8aa3b, v51
	v_exp_f32_e32 v69, v69
	s_nop 0
	v_add_f32_e32 v69, 1.0, v69
	v_rcp_f32_e32 v69, v69
	s_nop 0
	v_mul_f32_e32 v51, v51, v69
	v_mul_f32_e32 v50, v50, v51
	v_mov_b32_dpp v105, v97 row_ror:2 row_mask:0xf bank_mask:0xf
	v_mov_b32_dpp v115, v96 row_ror:2 row_mask:0xf bank_mask:0xf
	v_mov_b32_dpp v83, v97 row_ror:1 row_mask:0xf bank_mask:0xf
	v_mov_b32_dpp v111, v96 row_ror:1 row_mask:0xf bank_mask:0xf
	v_cndmask_b32_e64 v87, v101, v105, s[40:41]
	v_cndmask_b32_e64 v86, v103, v115, s[40:41]
	v_cndmask_b32_e64 v85, v83, v100, s[38:39]
	v_cndmask_b32_e64 v84, v111, v102, s[38:39]
	v_pk_fma_f32 v[86:87], v[36:37], v[86:87], v[38:39]
	v_pk_fma_f32 v[84:85], v[34:35], v[84:85], v[86:87]
	v_pk_fma_f32 v[84:85], v[40:41], v[96:97], v[84:85]
	v_mul_f32_e32 v51, 0xbfb8aa3b, v85
	v_exp_f32_e32 v51, v51
	s_nop 0
	v_add_f32_e32 v51, 1.0, v51
	v_rcp_f32_e32 v51, v51
	s_nop 0
	v_mul_f32_e32 v51, v85, v51
	v_mul_f32_e32 v51, v84, v51
	v_mov_b32_dpp v97, v81 row_ror:2 row_mask:0xf bank_mask:0xf
	v_mov_b32_dpp v101, v80 row_ror:2 row_mask:0xf bank_mask:0xf
	v_mov_b32_dpp v96, v81 row_ror:1 row_mask:0xf bank_mask:0xf
	v_mov_b32_dpp v100, v80 row_ror:1 row_mask:0xf bank_mask:0xf
	v_cndmask_b32_e64 v87, v105, v97, s[40:41]
	v_cndmask_b32_e64 v86, v115, v101, s[40:41]
	v_cndmask_b32_e64 v85, v96, v83, s[38:39]
	v_cndmask_b32_e64 v84, v100, v111, s[38:39]
	v_pk_fma_f32 v[86:87], v[36:37], v[86:87], v[38:39]
	v_pk_fma_f32 v[84:85], v[34:35], v[84:85], v[86:87]
	v_pk_fma_f32 v[80:81], v[40:41], v[80:81], v[84:85]
	v_mul_f32_e32 v69, 0xbfb8aa3b, v81
	v_exp_f32_e32 v69, v69
	s_nop 0
	v_add_f32_e32 v69, 1.0, v69
	v_rcp_f32_e32 v69, v69
	s_nop 0
	v_mul_f32_e32 v69, v81, v69
	v_mul_f32_e32 v69, v80, v69
	v_mov_b32_dpp v86, v67 row_ror:2 row_mask:0xf bank_mask:0xf
	v_mov_b32_dpp v102, v66 row_ror:2 row_mask:0xf bank_mask:0xf
	v_mov_b32_dpp v83, v67 row_ror:1 row_mask:0xf bank_mask:0xf
	v_mov_b32_dpp v87, v66 row_ror:1 row_mask:0xf bank_mask:0xf
	v_cndmask_b32_e64 v85, v97, v86, s[40:41]
	v_cndmask_b32_e64 v84, v101, v102, s[40:41]
	v_cndmask_b32_e64 v81, v83, v96, s[38:39]
	v_cndmask_b32_e64 v80, v87, v100, s[38:39]
	v_pk_fma_f32 v[84:85], v[36:37], v[84:85], v[38:39]
	v_pk_fma_f32 v[80:81], v[34:35], v[80:81], v[84:85]
	v_pk_fma_f32 v[66:67], v[40:41], v[66:67], v[80:81]
	v_mul_f32_e32 v80, 0xbfb8aa3b, v67
	v_exp_f32_e32 v80, v80
	s_nop 0
	v_add_f32_e32 v80, 1.0, v80
	v_rcp_f32_e32 v80, v80
	s_nop 0
	v_mul_f32_e32 v67, v67, v80
	v_mul_f32_e32 v66, v66, v67
	v_mov_b32_dpp v97, v49 row_ror:2 row_mask:0xf bank_mask:0xf
	v_mov_b32_dpp v101, v48 row_ror:2 row_mask:0xf bank_mask:0xf
	v_mov_b32_dpp v96, v49 row_ror:1 row_mask:0xf bank_mask:0xf
	v_mov_b32_dpp v100, v48 row_ror:1 row_mask:0xf bank_mask:0xf
	v_cndmask_b32_e64 v85, v86, v97, s[40:41]
	v_cndmask_b32_e64 v84, v102, v101, s[40:41]
	v_cndmask_b32_e64 v81, v96, v83, s[38:39]
	v_cndmask_b32_e64 v80, v100, v87, s[38:39]
	v_pk_fma_f32 v[84:85], v[36:37], v[84:85], v[38:39]
	v_pk_fma_f32 v[80:81], v[34:35], v[80:81], v[84:85]
	v_pk_fma_f32 v[48:49], v[40:41], v[48:49], v[80:81]
	v_mul_f32_e32 v67, 0xbfb8aa3b, v49
	v_exp_f32_e32 v67, v67
	s_nop 0
	v_add_f32_e32 v67, 1.0, v67
	v_rcp_f32_e32 v67, v67
	s_nop 0
	v_mul_f32_e32 v49, v49, v67
	v_mul_f32_e32 v48, v48, v49
	v_mov_b32_dpp v86, v33 row_ror:2 row_mask:0xf bank_mask:0xf
	v_mov_b32_dpp v102, v32 row_ror:2 row_mask:0xf bank_mask:0xf
	v_mov_b32_dpp v83, v33 row_ror:1 row_mask:0xf bank_mask:0xf
	v_mov_b32_dpp v87, v32 row_ror:1 row_mask:0xf bank_mask:0xf
	v_cndmask_b32_e64 v85, v97, v86, s[40:41]
	v_cndmask_b32_e64 v84, v101, v102, s[40:41]
	v_cndmask_b32_e64 v81, v83, v96, s[38:39]
	v_cndmask_b32_e64 v80, v87, v100, s[38:39]
	v_pk_fma_f32 v[84:85], v[36:37], v[84:85], v[38:39]
	s_nop 0
	v_pk_fma_f32 v[80:81], v[34:35], v[80:81], v[84:85]
	v_pk_fma_f32 v[32:33], v[40:41], v[32:33], v[80:81]
	v_mul_f32_e32 v49, 0xbfb8aa3b, v33
	v_exp_f32_e32 v49, v49
	s_nop 0
	v_add_f32_e32 v49, 1.0, v49
	v_rcp_f32_e32 v49, v49
	s_nop 0
	v_mul_f32_e32 v33, v33, v49
	v_mul_f32_e32 v49, v32, v33
	v_mov_b32_dpp v80, v27 row_ror:2 row_mask:0xf bank_mask:0xf
	v_mov_b32_dpp v81, v26 row_ror:1 row_mask:0xf bank_mask:0xf
	v_mov_b32_dpp v84, v26 row_ror:2 row_mask:0xf bank_mask:0xf
	v_mov_b32_dpp v67, v27 row_ror:1 row_mask:0xf bank_mask:0xf
	v_cndmask_b32_e64 v32, v81, v87, s[38:39]
	v_cndmask_b32_e64 v81, v86, v80, s[40:41]
	v_cndmask_b32_e64 v80, v102, v84, s[40:41]
	v_cndmask_b32_e64 v33, v67, v83, s[38:39]
	v_pk_fma_f32 v[36:37], v[36:37], v[80:81], v[38:39]
	s_nop 0
	v_pk_fma_f32 v[32:33], v[34:35], v[32:33], v[36:37]
	s_nop 0
	v_pk_fma_f32 v[26:27], v[40:41], v[26:27], v[32:33]
	s_nop 0
	v_mul_f32_e32 v32, 0xbfb8aa3b, v27
	v_exp_f32_e32 v32, v32
	s_nop 0
	v_add_f32_e32 v32, 1.0, v32
	v_rcp_f32_e32 v32, v32
	s_nop 0
	v_mul_f32_e32 v27, v27, v32
	v_mul_f32_e32 v38, v26, v27
	global_load_dword v33, v[6:7], off offset:24
	global_load_dword v27, v[8:9], off offset:2072
	global_load_dword v26, v[10:11], off offset:24
	global_load_dword v35, v[16:17], off offset:24
	global_load_dword v34, v[20:21], off offset:3096
	global_load_dword v32, v[18:19], off offset:3096
	global_load_dword v41, v[22:23], off offset:1048
	global_load_dword v40, v[24:25], off offset:3096
	v_mov_b32_dpp v67, v122 row_ror:1 row_mask:0xf bank_mask:0xf
	v_mov_b32_dpp v83, v122 row_ror:2 row_mask:0xf bank_mask:0xf
	v_cndmask_b32_e64 v123, v67, 0, s[38:39]
	v_cndmask_b32_e64 v36, 0, v83, s[40:41]
	v_mov_b32_dpp v84, v124 row_ror:1 row_mask:0xf bank_mask:0xf
	v_cndmask_b32_e64 v125, v84, 0, s[38:39]
	v_mov_b32_dpp v85, v124 row_ror:2 row_mask:0xf bank_mask:0xf
	v_cndmask_b32_e64 v39, 0, v85, s[40:41]
	s_waitcnt vmcnt(4)
; __device__ __forceinline__ float sigmoidf_(float x) { return __builtin_amdgcn_rcpf(1.0f + __expf(-x)); }
; template <int N> __device__ __forceinline__ float dpp_ror(float v) { return __builtin_bit_cast(float, __builtin_amdgcn_update_dpp(0, __builtin_bit_cast(int, v), 0x120 + N, 0xf, 0xf, false)); }
;     __device__ __forceinline__ void operator()(Acc& acc, const Unit& u, int wr, int wc, int fr, int fq) const {
;     ...
;             for (int i = 0; i < 4; ++i) {
;                 const int cg_ = ch0 + 4 * n + i, cv_ = DFF + cg_;
;                 const float g0 = cw[cg_], g1 = cw[NUP + cg_], g2 = cw[2 * NUP + cg_], gb = cb[cg_];
;                 const float v0 = cw[cv_], v1 = cw[NUP + cv_], v2 = cw[2 * NUP + cv_], vb = cb[cv_];
;                 float pg1 = 0.f, pg2 = 0.f, pv1 = 0.f, pv2 = 0.f;
; #pragma unroll
;                 for (int q = 0; q < 8; ++q) {
;                     float cgv = acc[q >> 2][0][q & 3][n][i], cvv = acc[q >> 2][1][q & 3][n][i];
;                     asm volatile("" : "+v"(cgv), "+v"(cvv) : "v"(chain));
;                     const float tg1 = dpp_ror<1>(cgv), tg2 = dpp_ror<2>(cgv), tv1 = dpp_ror<1>(cvv), tv2 = dpp_ror<2>(cvv);
;                     const float sg1 = fr >= 1 ? tg1 : pg1, sg2 = fr >= 2 ? tg2 : pg2, sv1 = fr >= 1 ? tv1 : pv1, sv2 = fr >= 2 ? tv2 : pv2;
;                     const float gg = gb + g0 * sg2 + g1 * sg1 + g2 * cgv;
;                     const float vv = vb + v0 * sv2 + v1 * sv1 + v2 * cvv;
;                     chain = gg * sigmoidf_(gg) * vv; acc[q >> 2][0][q & 3][n][i] = chain;
;                     pg1 = tg1; pg2 = tg2; pv1 = tv1; pv2 = tv2;
;                 }
	v_fma_f32 v80, v33, v36, v35
	v_pk_mul_f32 v[36:37], v[26:27], v[122:123]
	s_waitcnt vmcnt(2)
	v_fma_f32 v39, v32, v39, v34
	v_add_f32_e32 v37, v37, v80
	v_add_f32_e32 v100, v36, v37
	v_mul_f32_e32 v36, 0xbfb8aa3b, v100
	v_exp_f32_e32 v101, v36
	v_mov_b32_e32 v37, v26
	s_waitcnt vmcnt(0)
	v_pk_mul_f32 v[80:81], v[40:41], v[124:125]
	v_mov_b32_e32 v36, v40
	v_add_f32_e32 v26, 1.0, v101
	v_rcp_f32_e32 v40, v26
	v_add_f32_e32 v39, v81, v39
	v_add_f32_e32 v39, v80, v39
	v_mov_b32_e32 v26, v41
	v_mul_f32_e32 v40, v100, v40
	v_mul_f32_e32 v39, v39, v40
	v_mov_b32_dpp v87, v113 row_ror:2 row_mask:0xf bank_mask:0xf
	v_mov_b32_dpp v97, v112 row_ror:2 row_mask:0xf bank_mask:0xf
	v_mov_b32_dpp v86, v113 row_ror:1 row_mask:0xf bank_mask:0xf
	v_mov_b32_dpp v96, v112 row_ror:1 row_mask:0xf bank_mask:0xf
	v_cndmask_b32_e64 v81, v83, v87, s[40:41]
	v_cndmask_b32_e64 v80, v85, v97, s[40:41]
	v_cndmask_b32_e64 v41, v86, v67, s[38:39]
	v_cndmask_b32_e64 v40, v96, v84, s[38:39]
	v_pk_fma_f32 v[80:81], v[32:33], v[80:81], v[34:35]
	v_pk_fma_f32 v[40:41], v[26:27], v[40:41], v[80:81]
	s_nop 0
	v_pk_fma_f32 v[40:41], v[36:37], v[112:113], v[40:41]
	s_nop 0
	v_mul_f32_e32 v67, 0xbfb8aa3b, v41
	v_exp_f32_e32 v67, v67
	s_nop 0
	v_add_f32_e32 v67, 1.0, v67
	v_rcp_f32_e32 v67, v67
	s_nop 0
	v_mul_f32_e32 v41, v41, v67
	v_mul_f32_e32 v40, v40, v41
	v_mov_b32_dpp v100, v95 row_ror:2 row_mask:0xf bank_mask:0xf
	v_mov_b32_dpp v102, v94 row_ror:2 row_mask:0xf bank_mask:0xf
	v_mov_b32_dpp v83, v95 row_ror:1 row_mask:0xf bank_mask:0xf
	v_mov_b32_dpp v101, v94 row_ror:1 row_mask:0xf bank_mask:0xf
	v_cndmask_b32_e64 v85, v87, v100, s[40:41]
	v_cndmask_b32_e64 v84, v97, v102, s[40:41]
	v_cndmask_b32_e64 v81, v83, v86, s[38:39]
	v_cndmask_b32_e64 v80, v101, v96, s[38:39]
	v_pk_fma_f32 v[84:85], v[32:33], v[84:85], v[34:35]
	v_pk_fma_f32 v[80:81], v[26:27], v[80:81], v[84:85]
	v_pk_fma_f32 v[80:81], v[36:37], v[94:95], v[80:81]
	v_mul_f32_e32 v41, 0xbfb8aa3b, v81
	v_exp_f32_e32 v41, v41
	s_nop 0
	v_add_f32_e32 v41, 1.0, v41
	v_rcp_f32_e32 v41, v41
	s_nop 0
	v_mul_f32_e32 v41, v81, v41
	v_mul_f32_e32 v41, v80, v41
	v_mov_b32_dpp v87, v79 row_ror:2 row_mask:0xf bank_mask:0xf
	v_mov_b32_dpp v95, v78 row_ror:2 row_mask:0xf bank_mask:0xf
	v_mov_b32_dpp v86, v79 row_ror:1 row_mask:0xf bank_mask:0xf
	v_mov_b32_dpp v94, v78 row_ror:1 row_mask:0xf bank_mask:0xf
	v_cndmask_b32_e64 v85, v100, v87, s[40:41]
	v_cndmask_b32_e64 v84, v102, v95, s[40:41]
	v_cndmask_b32_e64 v81, v86, v83, s[38:39]
	v_cndmask_b32_e64 v80, v94, v101, s[38:39]
	v_pk_fma_f32 v[84:85], v[32:33], v[84:85], v[34:35]
	v_pk_fma_f32 v[80:81], v[26:27], v[80:81], v[84:85]
	v_pk_fma_f32 v[78:79], v[36:37], v[78:79], v[80:81]
	v_mul_f32_e32 v67, 0xbfb8aa3b, v79
	v_exp_f32_e32 v67, v67
	s_nop 0
	v_add_f32_e32 v67, 1.0, v67
	v_rcp_f32_e32 v67, v67
	s_nop 0
	v_mul_f32_e32 v67, v79, v67
	v_mul_f32_e32 v67, v78, v67
	v_mov_b32_dpp v84, v65 row_ror:2 row_mask:0xf bank_mask:0xf
	v_mov_b32_dpp v96, v64 row_ror:2 row_mask:0xf bank_mask:0xf
	v_mov_b32_dpp v83, v65 row_ror:1 row_mask:0xf bank_mask:0xf
	v_mov_b32_dpp v85, v64 row_ror:1 row_mask:0xf bank_mask:0xf
	v_cndmask_b32_e64 v81, v87, v84, s[40:41]
	v_cndmask_b32_e64 v80, v95, v96, s[40:41]
	v_cndmask_b32_e64 v79, v83, v86, s[38:39]
	v_cndmask_b32_e64 v78, v85, v94, s[38:39]
	v_pk_fma_f32 v[80:81], v[32:33], v[80:81], v[34:35]
	v_pk_fma_f32 v[78:79], v[26:27], v[78:79], v[80:81]
	v_pk_fma_f32 v[64:65], v[36:37], v[64:65], v[78:79]
	v_mul_f32_e32 v78, 0xbfb8aa3b, v65
	v_exp_f32_e32 v78, v78
	s_nop 0
	v_add_f32_e32 v78, 1.0, v78
	v_rcp_f32_e32 v78, v78
	s_nop 0
	v_mul_f32_e32 v65, v65, v78
	v_mul_f32_e32 v64, v64, v65
	v_mov_b32_dpp v87, v47 row_ror:2 row_mask:0xf bank_mask:0xf
	v_mov_b32_dpp v95, v46 row_ror:2 row_mask:0xf bank_mask:0xf
	v_mov_b32_dpp v86, v47 row_ror:1 row_mask:0xf bank_mask:0xf
	v_mov_b32_dpp v94, v46 row_ror:1 row_mask:0xf bank_mask:0xf
	v_cndmask_b32_e64 v81, v84, v87, s[40:41]
	v_cndmask_b32_e64 v80, v96, v95, s[40:41]
	v_cndmask_b32_e64 v79, v86, v83, s[38:39]
	v_cndmask_b32_e64 v78, v94, v85, s[38:39]
	v_pk_fma_f32 v[80:81], v[32:33], v[80:81], v[34:35]
	v_pk_fma_f32 v[78:79], v[26:27], v[78:79], v[80:81]
	v_pk_fma_f32 v[46:47], v[36:37], v[46:47], v[78:79]
	v_mul_f32_e32 v65, 0xbfb8aa3b, v47
	v_exp_f32_e32 v65, v65
	s_nop 0
	v_add_f32_e32 v65, 1.0, v65
	v_rcp_f32_e32 v65, v65
	s_nop 0
	v_mul_f32_e32 v47, v47, v65
	v_mul_f32_e32 v46, v46, v47
	v_mov_b32_dpp v84, v31 row_ror:2 row_mask:0xf bank_mask:0xf
	v_mov_b32_dpp v96, v30 row_ror:2 row_mask:0xf bank_mask:0xf
	v_mov_b32_dpp v83, v31 row_ror:1 row_mask:0xf bank_mask:0xf
	v_mov_b32_dpp v85, v30 row_ror:1 row_mask:0xf bank_mask:0xf
	v_cndmask_b32_e64 v81, v87, v84, s[40:41]
	v_cndmask_b32_e64 v80, v95, v96, s[40:41]
	v_cndmask_b32_e64 v79, v83, v86, s[38:39]
	v_cndmask_b32_e64 v78, v85, v94, s[38:39]
	v_pk_fma_f32 v[80:81], v[32:33], v[80:81], v[34:35]
	v_pk_fma_f32 v[78:79], v[26:27], v[78:79], v[80:81]
	v_pk_fma_f32 v[30:31], v[36:37], v[30:31], v[78:79]
	v_mul_f32_e32 v47, 0xbfb8aa3b, v31
	v_exp_f32_e32 v47, v47
	s_nop 0
	v_add_f32_e32 v47, 1.0, v47
	v_rcp_f32_e32 v47, v47
	s_nop 0
	v_mul_f32_e32 v31, v31, v47
	v_mul_f32_e32 v30, v30, v31
	v_mov_b32_dpp v80, v15 row_ror:2 row_mask:0xf bank_mask:0xf
	v_mov_b32_dpp v86, v14 row_ror:2 row_mask:0xf bank_mask:0xf
	v_mov_b32_dpp v65, v15 row_ror:1 row_mask:0xf bank_mask:0xf
	v_mov_b32_dpp v78, v14 row_ror:1 row_mask:0xf bank_mask:0xf
	v_cndmask_b32_e64 v81, v84, v80, s[40:41]
	v_cndmask_b32_e64 v80, v96, v86, s[40:41]
	v_cndmask_b32_e64 v79, v65, v83, s[38:39]
	v_cndmask_b32_e64 v78, v78, v85, s[38:39]
	v_pk_fma_f32 v[32:33], v[32:33], v[80:81], v[34:35]
	s_nop 0
	v_pk_fma_f32 v[26:27], v[26:27], v[78:79], v[32:33]
	s_nop 0
	v_pk_fma_f32 v[14:15], v[36:37], v[14:15], v[26:27]
	s_nop 0
	v_mul_f32_e32 v26, 0xbfb8aa3b, v15
	v_exp_f32_e32 v26, v26
	s_nop 0
	v_add_f32_e32 v26, 1.0, v26
	v_rcp_f32_e32 v26, v26
	s_nop 0
	v_mul_f32_e32 v15, v15, v26
	v_mul_f32_e32 v26, v14, v15
	global_load_dword v15, v[6:7], off offset:28
	s_nop 0
	global_load_dword v7, v[8:9], off offset:2076
	global_load_dword v6, v[10:11], off offset:28
	s_nop 0
	global_load_dword v9, v[16:17], off offset:28
	global_load_dword v14, v[18:19], off offset:3100
	s_nop 0
	global_load_dword v17, v[22:23], off offset:1052
	global_load_dword v16, v[24:25], off offset:3100
	global_load_dword v8, v[20:21], off offset:3100
	v_mov_b32_dpp v19, v120 row_ror:1 row_mask:0xf bank_mask:0xf
	v_mov_b32_dpp v22, v120 row_ror:2 row_mask:0xf bank_mask:0xf
	v_cndmask_b32_e64 v121, v19, 0, s[38:39]
	v_cndmask_b32_e64 v10, 0, v22, s[40:41]
	v_mov_b32_dpp v20, v110 row_ror:1 row_mask:0xf bank_mask:0xf
	v_mov_b32_dpp v24, v110 row_ror:2 row_mask:0xf bank_mask:0xf
	v_cndmask_b32_e64 v111, v20, 0, s[38:39]
	v_cndmask_b32_e64 v18, 0, v24, s[40:41]
	v_mov_b32_e32 v35, v3
	v_mov_b32_e32 v36, v3
	s_waitcnt vmcnt(4)
; __device__ __forceinline__ unsigned pk2(float lo, float hi) { const f32x2_t v = {lo, hi}; const bf16x2_t b = __builtin_convertvector(v, bf16x2_t); return __builtin_bit_cast(unsigned, b); }
; __device__ __forceinline__ float sigmoidf_(float x) { return __builtin_amdgcn_rcpf(1.0f + __expf(-x)); }
; template <int N> __device__ __forceinline__ float dpp_ror(float v) { return __builtin_bit_cast(float, __builtin_amdgcn_update_dpp(0, __builtin_bit_cast(int, v), 0x120 + N, 0xf, 0xf, false)); }
;     __device__ __forceinline__ void operator()(Acc& acc, const Unit& u, int wr, int wc, int fr, int fq) const {
;     ...
;             for (int i = 0; i < 4; ++i) {
;                 const int cg_ = ch0 + 4 * n + i, cv_ = DFF + cg_;
;                 const float g0 = cw[cg_], g1 = cw[NUP + cg_], g2 = cw[2 * NUP + cg_], gb = cb[cg_];
;                 const float v0 = cw[cv_], v1 = cw[NUP + cv_], v2 = cw[2 * NUP + cv_], vb = cb[cv_];
;                 float pg1 = 0.f, pg2 = 0.f, pv1 = 0.f, pv2 = 0.f;
; #pragma unroll
;                 for (int q = 0; q < 8; ++q) {
;                     float cgv = acc[q >> 2][0][q & 3][n][i], cvv = acc[q >> 2][1][q & 3][n][i];
;                     asm volatile("" : "+v"(cgv), "+v"(cvv) : "v"(chain));
;                     const float tg1 = dpp_ror<1>(cgv), tg2 = dpp_ror<2>(cgv), tv1 = dpp_ror<1>(cvv), tv2 = dpp_ror<2>(cvv);
;                     const float sg1 = fr >= 1 ? tg1 : pg1, sg2 = fr >= 2 ? tg2 : pg2, sv1 = fr >= 1 ? tv1 : pv1, sv2 = fr >= 2 ? tv2 : pv2;
;                     const float gg = gb + g0 * sg2 + g1 * sg1 + g2 * cgv;
;                     const float vv = vb + v0 * sv2 + v1 * sv1 + v2 * cvv;
;                     chain = gg * sigmoidf_(gg) * vv; acc[q >> 2][0][q & 3][n][i] = chain;
;                     pg1 = tg1; pg2 = tg2; pv1 = tv1; pv2 = tv2;
;                 }
;                 __builtin_amdgcn_sched_barrier(0);
;             }
;         }
; #pragma unroll
;         for (int q = 0; q < 8; ++q) {
;             const int t = tbase + 16 * q;
;             if ((16 * q + fr >= 2) && (t < SEQ)) {
;                 const f32x4 a0 = acc[q >> 2][0][q & 3][0], a1 = acc[q >> 2][0][q & 3][1];
;                 u32x4 w; w.x = pk2(a0[0], a0[1]); w.y = pk2(a0[2], a0[3]); w.z = pk2(a1[0], a1[1]); w.w = pk2(a1[2], a1[3]);
;                 *(u32x4*)(act + (size_t)(b * SEQ + t) * DFF + ch0) = w;
;             }
	v_fma_f32 v21, v15, v10, v9
	v_pk_mul_f32 v[10:11], v[6:7], v[120:121]
	s_waitcnt vmcnt(0)
	v_fma_f32 v18, v14, v18, v8
	v_add_f32_e32 v11, v11, v21
	v_add_f32_e32 v21, v10, v11
	v_pk_mul_f32 v[10:11], v[16:17], v[110:111]
	s_nop 0
	v_add_f32_e32 v11, v11, v18
	v_add_f32_e32 v10, v10, v11
	v_mul_f32_e32 v11, 0xbfb8aa3b, v21
	v_exp_f32_e32 v11, v11
	s_nop 0
	v_add_f32_e32 v11, 1.0, v11
	v_rcp_f32_e32 v11, v11
	s_nop 0
	v_mul_f32_e32 v11, v21, v11
	v_mul_f32_e32 v18, v10, v11
	v_mov_b32_e32 v11, v6
	v_mov_b32_e32 v6, v17
	v_mov_b32_dpp v27, v109 row_ror:2 row_mask:0xf bank_mask:0xf
	v_mov_b32_dpp v32, v108 row_ror:2 row_mask:0xf bank_mask:0xf
	v_mov_b32_dpp v25, v109 row_ror:1 row_mask:0xf bank_mask:0xf
	v_mov_b32_dpp v31, v108 row_ror:1 row_mask:0xf bank_mask:0xf
	v_cndmask_b32_e64 v23, v22, v27, s[40:41]
	v_cndmask_b32_e64 v22, v24, v32, s[40:41]
	v_cndmask_b32_e64 v21, v25, v19, s[38:39]
	v_cndmask_b32_e64 v20, v31, v20, s[38:39]
	v_pk_fma_f32 v[22:23], v[14:15], v[22:23], v[8:9]
	v_mov_b32_e32 v10, v16
	v_pk_fma_f32 v[16:17], v[6:7], v[20:21], v[22:23]
	v_pk_fma_f32 v[16:17], v[10:11], v[108:109], v[16:17]
	s_nop 0
	v_mul_f32_e32 v19, 0xbfb8aa3b, v17
	v_exp_f32_e32 v19, v19
	s_nop 0
	v_add_f32_e32 v19, 1.0, v19
	v_rcp_f32_e32 v19, v19
	s_nop 0
	v_mul_f32_e32 v17, v17, v19
	v_mul_f32_e32 v16, v16, v17
	v_mov_b32_dpp v24, v93 row_ror:2 row_mask:0xf bank_mask:0xf
	v_mov_b32_dpp v34, v92 row_ror:2 row_mask:0xf bank_mask:0xf
	v_mov_b32_dpp v19, v93 row_ror:1 row_mask:0xf bank_mask:0xf
	v_mov_b32_dpp v33, v92 row_ror:1 row_mask:0xf bank_mask:0xf
	v_cndmask_b32_e64 v23, v27, v24, s[40:41]
	v_cndmask_b32_e64 v22, v32, v34, s[40:41]
	v_cndmask_b32_e64 v21, v19, v25, s[38:39]
	v_cndmask_b32_e64 v20, v33, v31, s[38:39]
	v_pk_fma_f32 v[22:23], v[14:15], v[22:23], v[8:9]
	v_pk_fma_f32 v[20:21], v[6:7], v[20:21], v[22:23]
	v_pk_fma_f32 v[20:21], v[10:11], v[92:93], v[20:21]
	v_mul_f32_e32 v17, 0xbfb8aa3b, v21
	v_exp_f32_e32 v17, v17
	s_nop 0
	v_add_f32_e32 v17, 1.0, v17
	v_rcp_f32_e32 v17, v17
	s_nop 0
	v_mul_f32_e32 v17, v21, v17
	v_mul_f32_e32 v17, v20, v17
	v_mov_b32_dpp v27, v77 row_ror:2 row_mask:0xf bank_mask:0xf
	v_mov_b32_dpp v32, v76 row_ror:2 row_mask:0xf bank_mask:0xf
	v_mov_b32_dpp v25, v77 row_ror:1 row_mask:0xf bank_mask:0xf
	v_mov_b32_dpp v31, v76 row_ror:1 row_mask:0xf bank_mask:0xf
	v_cndmask_b32_e64 v23, v24, v27, s[40:41]
	v_cndmask_b32_e64 v22, v34, v32, s[40:41]
	v_cndmask_b32_e64 v21, v25, v19, s[38:39]
	v_cndmask_b32_e64 v20, v31, v33, s[38:39]
	v_pk_fma_f32 v[22:23], v[14:15], v[22:23], v[8:9]
	v_pk_fma_f32 v[20:21], v[6:7], v[20:21], v[22:23]
	v_pk_fma_f32 v[20:21], v[10:11], v[76:77], v[20:21]
	v_mul_f32_e32 v19, 0xbfb8aa3b, v21
	v_exp_f32_e32 v19, v19
	s_nop 0
	v_add_f32_e32 v19, 1.0, v19
	v_rcp_f32_e32 v19, v19
	s_nop 0
	v_mul_f32_e32 v19, v21, v19
	v_mul_f32_e32 v19, v20, v19
	v_mov_b32_dpp v33, v61 row_ror:2 row_mask:0xf bank_mask:0xf
	v_mov_b32_dpp v35, v60 row_ror:2 row_mask:0xf bank_mask:0xf
	v_mov_b32_dpp v24, v61 row_ror:1 row_mask:0xf bank_mask:0xf
	v_mov_b32_dpp v34, v60 row_ror:1 row_mask:0xf bank_mask:0xf
	v_cndmask_b32_e64 v23, v27, v33, s[40:41]
	v_cndmask_b32_e64 v22, v32, v35, s[40:41]
	v_cndmask_b32_e64 v21, v24, v25, s[38:39]
	v_cndmask_b32_e64 v20, v34, v31, s[38:39]
	v_pk_fma_f32 v[22:23], v[14:15], v[22:23], v[8:9]
	v_pk_fma_f32 v[20:21], v[6:7], v[20:21], v[22:23]
	v_pk_fma_f32 v[20:21], v[10:11], v[60:61], v[20:21]
	v_mul_f32_e32 v22, 0xbfb8aa3b, v21
	v_exp_f32_e32 v22, v22
	s_nop 0
	v_add_f32_e32 v22, 1.0, v22
	v_rcp_f32_e32 v22, v22
	s_nop 0
	v_mul_f32_e32 v21, v21, v22
	v_mul_f32_e32 v20, v20, v21
	v_mov_b32_dpp v27, v45 row_ror:1 row_mask:0xf bank_mask:0xf
	v_mov_b32_dpp v31, v45 row_ror:2 row_mask:0xf bank_mask:0xf
	v_mov_b32_dpp v36, v44 row_ror:2 row_mask:0xf bank_mask:0xf
	v_mov_b32_dpp v32, v44 row_ror:1 row_mask:0xf bank_mask:0xf
	v_cndmask_b32_e64 v23, v27, v24, s[38:39]
	v_cndmask_b32_e64 v25, v33, v31, s[40:41]
	v_cndmask_b32_e64 v24, v35, v36, s[40:41]
	v_cndmask_b32_e64 v22, v32, v34, s[38:39]
	v_pk_fma_f32 v[24:25], v[14:15], v[24:25], v[8:9]
	s_nop 0
	v_pk_fma_f32 v[22:23], v[6:7], v[22:23], v[24:25]
	v_pk_fma_f32 v[22:23], v[10:11], v[44:45], v[22:23]
	s_nop 0
	v_mul_f32_e32 v21, 0xbfb8aa3b, v23
	v_exp_f32_e32 v21, v21
	s_nop 0
	v_add_f32_e32 v21, 1.0, v21
	v_rcp_f32_e32 v21, v21
	s_nop 0
	v_mul_f32_e32 v21, v23, v21
	v_mul_f32_e32 v24, v22, v21
	v_mov_b32_dpp v22, v29 row_ror:2 row_mask:0xf bank_mask:0xf
	v_mov_b32_dpp v25, v28 row_ror:2 row_mask:0xf bank_mask:0xf
	v_mov_b32_dpp v21, v29 row_ror:1 row_mask:0xf bank_mask:0xf
	v_mov_b32_dpp v23, v28 row_ror:1 row_mask:0xf bank_mask:0xf
	v_cndmask_b32_e64 v35, v31, v22, s[40:41]
	v_cndmask_b32_e64 v34, v36, v25, s[40:41]
	v_cndmask_b32_e64 v33, v21, v27, s[38:39]
	v_cndmask_b32_e64 v32, v23, v32, s[38:39]
	v_pk_fma_f32 v[34:35], v[14:15], v[34:35], v[8:9]
	v_pk_fma_f32 v[32:33], v[6:7], v[32:33], v[34:35]
	s_nop 0
	v_pk_fma_f32 v[28:29], v[10:11], v[28:29], v[32:33]
	v_mul_f32_e32 v27, 0xbfb8aa3b, v29
	v_exp_f32_e32 v27, v27
	s_nop 0
	v_add_f32_e32 v27, 1.0, v27
	v_rcp_f32_e32 v27, v27
	s_nop 0
	v_mul_f32_e32 v27, v29, v27
	v_mul_f32_e32 v27, v28, v27
	s_nop 0
	v_mov_b32_dpp v28, v13 row_ror:1 row_mask:0xf bank_mask:0xf
	v_mov_b32_dpp v29, v13 row_ror:2 row_mask:0xf bank_mask:0xf
	v_mov_b32_dpp v31, v12 row_ror:1 row_mask:0xf bank_mask:0xf
	v_mov_b32_dpp v32, v12 row_ror:2 row_mask:0xf bank_mask:0xf
	v_cmp_gt_i32_e32 vcc, s97, v198
	s_and_b64 s[44:45], s[40:41], vcc
	s_and_saveexec_b64 s[34:35], s[44:45]
	s_cbranch_execz .LBB0_45
	v_cvt_pk_bf16_f32 v37, v39, v18
	v_add_u32_e32 v18, s20, v198
	v_mov_b64_e32 v[44:45], s[8:9]
	s_movk_i32 s21, 0x1600
	v_mad_i64_i32 v[44:45], s[44:45], v18, s21, v[44:45]
	v_cvt_pk_bf16_f32 v34, v184, v137
	v_cvt_pk_bf16_f32 v35, v99, v63
	v_cvt_pk_bf16_f32 v36, v56, v43
	v_lshl_add_u64 v[44:45], v[4:5], 1, v[44:45]
	flat_store_dwordx4 v[44:45], v[34:37]
